# hot loop heads (8 K-loops and the MLA key-tile loop) aligned to 64-byte instruction-cache lines
# speedup vs baseline: 1.0025x; 1.0013x over previous
; DI int TID() { int t = (int)__builtin_amdgcn_workitem_id_x(); asm volatile("" : "+v"(t)); return t; }
; #define BLOAD(A_, B_, kt) do { _Pragma("unroll") for (int i = 0; i < 4; ++i) { \
;     A_[i] = *(const u32x4*)((const char*)Ap + (aoff + (unsigned)(32 * i * lda + (kt) * 64) * 2u)); B_[i] = *(const u32x4*)((const char*)Wt + (woff + (unsigned)(32 * i * K + (kt) * 64) * 2u)); } } while (0)
; #define BLOAD(A_, B_, kt) do { _Pragma("unroll") for (int i = 0; i < 4; ++i) { \
;     A_[i] = *(const u32x4*)((const char*)Ap + (aoff + (unsigned)(32 * i * lda + (kt) * 64) * 2u)); B_[i] = *(const u32x4*)((const char*)Wt + (woff + (unsigned)(32 * i * K + (kt) * 64) * 2u)); } } while (0)
; #define BSTORE(A_, B_, buf) do { _Pragma("unroll") for (int i = 0; i < 4; ++i) { \
;     *(u32x4*)&As[(buf) * GBUF + (srow + 32 * i) * LDT + sc8] = A_[i]; \
;     *(u32x4*)&Bs[(buf) * GBUF + (srow + 32 * i) * LDT + sc8] = B_[i]; } } while (0)
; template <int NK>
; DI void gemm_run(PF& pf, const u16* __restrict__ Ap, int lda, const u16* __restrict__ Wt, f32x16 (&acc)[2][2], char* smem) {
;   constexpr int K = NK * 64;
;   const int tid = TID(), lane = tid & 63, w = tid >> 6, wm = w >> 1, wn = w & 1, r32 = lane & 31, hi = lane >> 5;
;   u16* As = (u16*)smem; u16* Bs = As + 128 * LDT;
;   const int srow = tid >> 3, sc8 = (tid & 7) * 8;
;   constexpr int nk = NK;
;   const unsigned aoff = (unsigned)(srow * lda + sc8) * 2u, woff = (unsigned)(srow * K + sc8) * 2u;
;     ...
;   __builtin_amdgcn_s_setprio(0);
;   __syncthreads();
;   BSTORE(pf.a0, pf.b0, 0);
;   BLOAD(pf.a0, pf.b0, 2);
;   __syncthreads();
; DI void tile_ffn2(const Params& p, int l, const Chunk& ck, int tile, int next, PF& pf, char* smem) {
;   float* Cs = (float*)smem;
;   const int tid = TID(); const int mi = tile & (MTN - 1), ni = tile >> MTS; const int m0 = mi * 128, n0 = ni * 128;
;   f32x16 acc[2][2]; zero_acc(acc);
;   { const u16* Ap; const u16* Wt; ffn2_ptrs(p, l, tile, Ap, Wt); gemm_run<64>(pf, Ap, 4096, Wt, acc, smem); }
.LBB1_206:
	s_add_i32 s25, s26, s78
	s_cmpk_gt_i32 s25, 0x1ff
	s_cselect_b64 s[28:29], -1, 0
	s_cmpk_lt_i32 s25, 0x200
	s_cselect_b32 s0, s25, -1
	s_and_b32 s16, s41, 0x3f80000
	s_and_b32 s36, s26, 0xffffff80
	s_add_i32 s26, s26, s36
	s_lshl_b32 s36, s36, 1
	s_lshl_b32 s16, s16, 1
	s_add_u32 vcc_lo, s17, s16
	v_mov_b32_e32 v0, v172
	s_addc_u32 vcc_hi, s27, 0
	s_ashr_i32 s37, s36, 31
	s_lshl_b64 s[30:31], s[36:37], 6
	s_add_u32 s30, s34, s30
	s_addc_u32 s31, s40, s31
	s_setprio 0
	s_waitcnt lgkmcnt(0)
	s_lshr_b32 s16, s16, 7
	s_add_u32 s42, s17, s16
	s_addc_u32 s43, s27, 0
	v_and_b32_e32 v174, 63, v172
	v_lshrrev_b32_e32 v175, 6, v172
	v_bfe_u32 v176, v174, 4, 2
	v_lshrrev_b32_e32 v177, 1, v176
	v_xor_b32_e32 v176, v176, v177
	v_and_b32_e32 v176, 1, v176
	v_lshl_or_b32 v176, v176, 1, v177
	v_xor_b32_e32 v176, v176, v174
	v_and_b32_e32 v176, 3, v176
	v_lshlrev_b32_e32 v176, 4, v176
	v_lshrrev_b32_e32 v177, 2, v174
	v_lshl_add_u32 v137, v175, 5, v177
	v_lshl_add_u32 v137, v137, 6, v176
	v_mov_b32_e32 v150, v137
	v_lshl_add_u32 v151, v175, 6, v177
	v_lshl_add_u32 v151, v151, 6, v176
	v_mov_b32_e32 v152, v151
	v_mov_b32_e32 v153, v151
	v_mov_b32_e32 v154, v151
	v_readfirstlane_b32 s16, v175
	s_lshl_b32 s0, s16, 12
	s_lshl_b32 s16, s16, 11
	s_add_u32 s0, s0, 0x2000
	v_bfe_u32 v176, v174, 2, 2
	v_lshrrev_b32_e32 v177, 1, v176
	v_xor_b32_e32 v176, v176, v177
	v_and_b32_e32 v176, 1, v176
	v_lshl_or_b32 v176, v176, 1, v177
	v_lshrrev_b32_e32 v177, 4, v174
	v_xor_b32_e32 v176, v176, v177
	v_lshlrev_b32_e32 v176, 4, v176
	v_and_b32_e32 v174, 15, v174
	v_lshl_add_u32 v174, v174, 6, v176
	v_lshrrev_b32_e32 v176, 1, v175
	v_and_b32_e32 v177, 1, v175
	v_lshl_add_u32 v126, v176, 12, v174
	v_lshl_add_u32 v128, v177, 12, v174
	v_add_u32_e32 v128, 0x2000, v128
	s_barrier
	v_mov_b32_e32 v2, 0
	v_mov_b32_e32 v3, 0
	v_mov_b32_e32 v4, 0
	v_mov_b32_e32 v5, 0
	v_mov_b32_e32 v6, 0
	v_mov_b32_e32 v7, 0
	v_mov_b32_e32 v8, 0
	v_mov_b32_e32 v9, 0
	v_mov_b32_e32 v10, 0
	v_mov_b32_e32 v11, 0
	v_mov_b32_e32 v12, 0
	v_mov_b32_e32 v13, 0
	v_mov_b32_e32 v14, 0
	v_mov_b32_e32 v15, 0
	v_mov_b32_e32 v16, 0
	v_mov_b32_e32 v17, 0
	v_mov_b32_e32 v18, 0
	v_mov_b32_e32 v19, 0
	v_mov_b32_e32 v20, 0
	v_mov_b32_e32 v21, 0
	v_mov_b32_e32 v22, 0
	v_mov_b32_e32 v23, 0
	v_mov_b32_e32 v24, 0
	v_mov_b32_e32 v25, 0
	v_mov_b32_e32 v26, 0
	v_mov_b32_e32 v27, 0
	v_mov_b32_e32 v28, 0
	v_mov_b32_e32 v29, 0
	v_mov_b32_e32 v30, 0
	v_mov_b32_e32 v31, 0
	v_mov_b32_e32 v32, 0
	v_mov_b32_e32 v33, 0
	v_mov_b32_e32 v34, 0
	v_mov_b32_e32 v35, 0
	v_mov_b32_e32 v36, 0
	v_mov_b32_e32 v37, 0
	v_mov_b32_e32 v38, 0
	v_mov_b32_e32 v39, 0
	v_mov_b32_e32 v40, 0
	v_mov_b32_e32 v41, 0
	v_mov_b32_e32 v42, 0
	v_mov_b32_e32 v43, 0
	v_mov_b32_e32 v44, 0
	v_mov_b32_e32 v45, 0
	v_mov_b32_e32 v46, 0
	v_mov_b32_e32 v47, 0
	v_mov_b32_e32 v48, 0
	v_mov_b32_e32 v49, 0
	v_mov_b32_e32 v50, 0
	v_mov_b32_e32 v51, 0
	v_mov_b32_e32 v52, 0
	v_mov_b32_e32 v53, 0
	v_mov_b32_e32 v54, 0
	v_mov_b32_e32 v55, 0
	v_mov_b32_e32 v56, 0
	v_mov_b32_e32 v57, 0
	v_mov_b32_e32 v58, 0
	v_mov_b32_e32 v59, 0
	v_mov_b32_e32 v60, 0
	v_mov_b32_e32 v61, 0
	v_mov_b32_e32 v62, 0
	v_mov_b32_e32 v63, 0
	v_mov_b32_e32 v64, 0
	v_mov_b32_e32 v65, 0
	v_mov_b32_e32 v74, 0
	v_mov_b32_e32 v75, 0
	v_mov_b32_e32 v76, 0
	v_mov_b32_e32 v77, 0
	v_mov_b32_e32 v78, 0
	v_mov_b32_e32 v79, 0
	v_mov_b32_e32 v80, 0
	v_mov_b32_e32 v81, 0
	v_mov_b32_e32 v82, 0
	v_mov_b32_e32 v83, 0
	v_mov_b32_e32 v84, 0
	v_mov_b32_e32 v85, 0
	v_mov_b32_e32 v86, 0
	v_mov_b32_e32 v87, 0
	v_mov_b32_e32 v88, 0
	v_mov_b32_e32 v89, 0
	v_mov_b32_e32 v90, 0
	v_mov_b32_e32 v91, 0
	v_mov_b32_e32 v92, 0
	v_mov_b32_e32 v93, 0
	v_mov_b32_e32 v94, 0
	v_mov_b32_e32 v95, 0
	v_mov_b32_e32 v96, 0
	v_mov_b32_e32 v97, 0
	v_mov_b32_e32 v98, 0
	v_mov_b32_e32 v99, 0
	v_mov_b32_e32 v100, 0
	v_mov_b32_e32 v101, 0
	v_mov_b32_e32 v102, 0
	v_mov_b32_e32 v103, 0
	v_mov_b32_e32 v104, 0
	v_mov_b32_e32 v105, 0
	v_mov_b32_e32 v106, 0
	v_mov_b32_e32 v107, 0
	v_mov_b32_e32 v108, 0
	v_mov_b32_e32 v109, 0
	v_mov_b32_e32 v110, 0
	v_mov_b32_e32 v111, 0
	v_mov_b32_e32 v112, 0
	v_mov_b32_e32 v113, 0
	v_mov_b32_e32 v114, 0
	v_mov_b32_e32 v115, 0
	v_mov_b32_e32 v116, 0
	v_mov_b32_e32 v117, 0
	v_mov_b32_e32 v118, 0
	v_mov_b32_e32 v119, 0
	v_mov_b32_e32 v120, 0
	v_mov_b32_e32 v121, 0
	v_mov_b32_e32 v208, 0
	v_mov_b32_e32 v209, 0
	v_mov_b32_e32 v210, 0
	v_mov_b32_e32 v211, 0
	v_mov_b32_e32 v212, 0
	v_mov_b32_e32 v213, 0
	v_mov_b32_e32 v214, 0
	v_mov_b32_e32 v215, 0
	v_mov_b32_e32 v216, 0
	v_mov_b32_e32 v217, 0
	v_mov_b32_e32 v218, 0
	v_mov_b32_e32 v219, 0
	v_mov_b32_e32 v220, 0
	v_mov_b32_e32 v221, 0
	v_mov_b32_e32 v222, 0
	v_mov_b32_e32 v223, 0
	s_add_u32 m0, s16, 0x0
	s_nop 0
	global_load_lds_dwordx4 v137, s[42:43]
	global_load_lds_dwordx4 v150, s[42:43] offset:1024
	s_add_u32 m0, s0, 0x0
	s_nop 0
	global_load_lds_dwordx4 v151, s[30:31]
	global_load_lds_dwordx4 v152, s[30:31] offset:1024
	global_load_lds_dwordx4 v153, s[30:31] offset:2048
	global_load_lds_dwordx4 v154, s[30:31] offset:3072
	s_add_u32 m0, s16, 0x6000
	s_add_u32 s42, s42, 0x100000
	s_addc_u32 s43, s43, 0
	global_load_lds_dwordx4 v137, s[42:43]
	global_load_lds_dwordx4 v150, s[42:43] offset:1024
	s_add_u32 m0, s0, 0x6000
	s_add_u32 s30, s30, 0x10000
	s_addc_u32 s31, s31, 0
	global_load_lds_dwordx4 v151, s[30:31]
	global_load_lds_dwordx4 v152, s[30:31] offset:1024
	global_load_lds_dwordx4 v153, s[30:31] offset:2048
	global_load_lds_dwordx4 v154, s[30:31] offset:3072
	s_mov_b32 s46, 42
	.p2align 6

; DI int TID() { int t = (int)__builtin_amdgcn_workitem_id_x(); asm volatile("" : "+v"(t)); return t; }
; #define BLOAD(A_, B_, kt) do { _Pragma("unroll") for (int i = 0; i < 4; ++i) { \
;     A_[i] = *(const u32x4*)((const char*)Ap + (aoff + (unsigned)(32 * i * lda + (kt) * 64) * 2u)); B_[i] = *(const u32x4*)((const char*)Wt + (woff + (unsigned)(32 * i * K + (kt) * 64) * 2u)); } } while (0)
; DI RowSS rowss_load(const float* ps, int m0) { const int tid = TID(); const float* q = ps + (size_t)(m0 + (tid >> 1)) * 16 + (tid & 1) * 8; RowSS r; r.a = *(const f32x4*)q; r.b = *(const f32x4*)(q + 4); return r; }
; #define BLOAD(A_, B_, kt) do { _Pragma("unroll") for (int i = 0; i < 4; ++i) { \
;     A_[i] = *(const u32x4*)((const char*)Ap + (aoff + (unsigned)(32 * i * lda + (kt) * 64) * 2u)); B_[i] = *(const u32x4*)((const char*)Wt + (woff + (unsigned)(32 * i * K + (kt) * 64) * 2u)); } } while (0)
; #define BSTORE(A_, B_, buf) do { _Pragma("unroll") for (int i = 0; i < 4; ++i) { \
;     *(u32x4*)&As[(buf) * GBUF + (srow + 32 * i) * LDT + sc8] = A_[i]; \
;     *(u32x4*)&Bs[(buf) * GBUF + (srow + 32 * i) * LDT + sc8] = B_[i]; } } while (0)
; template <int NK>
; DI void gemm_run(PF& pf, const u16* __restrict__ Ap, int lda, const u16* __restrict__ Wt, f32x16 (&acc)[2][2], char* smem) {
;   constexpr int K = NK * 64;
;   const int tid = TID(), lane = tid & 63, w = tid >> 6, wm = w >> 1, wn = w & 1, r32 = lane & 31, hi = lane >> 5;
;   u16* As = (u16*)smem; u16* Bs = As + 128 * LDT;
;   const int srow = tid >> 3, sc8 = (tid & 7) * 8;
;   constexpr int nk = NK;
;   const unsigned aoff = (unsigned)(srow * lda + sc8) * 2u, woff = (unsigned)(srow * K + sc8) * 2u;
;     ...
;   __builtin_amdgcn_s_setprio(0);
;   __syncthreads();
;   BSTORE(pf.a0, pf.b0, 0);
;   BLOAD(pf.a0, pf.b0, 2);
;   __syncthreads();
; DI void tile_ffn1(const Params& p, int l, const Chunk& ck, int tile, int next, PF& pf, char* smem) {
;   float* Cs = (float*)smem; float* rinv_s = (float*)(smem + SMEM_CS);
;   const int tid = TID(); const int mi = tile & (MTN - 1), ni = tile >> MTS; const int m0 = mi * 128, n0 = ni * 128;
;   f32x16 acc[2][2]; zero_acc(acc);
;   const RowSS rss = rowss_load((const float*)(p.ws + OFF_PSMID), m0);
;   { const u16* Ap; const u16* Wt; ffn1_ptrs(p, l, tile, Ap, Wt); gemm_run<16>(pf, Ap, 1024, Wt, acc, smem); }
.LBB1_246:
	s_mov_b32 s26, s16
	s_add_i32 s16, s16, s78
	s_cmpk_gt_i32 s16, 0x7ff
	s_cselect_b64 s[24:25], -1, 0
	s_cmpk_lt_i32 s16, 0x800
	v_mov_b32_e32 v148, v172
	v_mov_b32_e32 v0, v172
	s_cselect_b32 s0, s16, -1
	s_and_b32 s41, s40, 0x3f80
	s_and_b32 s27, s35, 0xfe0000
	v_ashrrev_i32_e32 v2, 1, v0
	v_add_u32_e32 v2, s41, v2
	v_ashrrev_i32_e32 v3, 31, v2
	v_lshlrev_b64 v[2:3], 6, v[2:3]
	v_lshlrev_b32_e32 v0, 5, v0
	v_lshl_add_u64 v[2:3], s[20:21], 0, v[2:3]
	v_and_b32_e32 v0, 32, v0
	v_lshl_add_u64 v[2:3], v[2:3], 0, v[0:1]
	global_load_dwordx4 v[66:69], v[2:3], off offset:16
	global_load_dwordx4 v[70:73], v[2:3], off
	s_and_b32 s26, s26, 0xffffff80
	s_lshl_b32 s26, s26, 1
	s_lshr_b32 s27, s27, 4
	s_add_u32 s28, s17, s27
	s_addc_u32 s29, s34, 0
	s_ashr_i32 s27, s26, 31
	s_lshl_b64 s[30:31], s[26:27], 6
	s_add_u32 s30, s36, s30
	s_addc_u32 s31, s37, s31
	s_setprio 0
	s_waitcnt lgkmcnt(0)
	s_mov_b32 s0, 0
	v_and_b32_e32 v149, 63, v172
	v_lshrrev_b32_e32 v151, 6, v172
	v_bfe_u32 v152, v149, 4, 2
	v_lshrrev_b32_e32 v153, 1, v152
	v_xor_b32_e32 v152, v152, v153
	v_and_b32_e32 v152, 1, v152
	v_lshl_or_b32 v152, v152, 1, v153
	v_xor_b32_e32 v152, v152, v149
	v_and_b32_e32 v152, 3, v152
	v_lshlrev_b32_e32 v152, 4, v152
	v_lshrrev_b32_e32 v153, 2, v149
	v_lshl_add_u32 v142, v151, 5, v153
	v_lshl_add_u32 v142, v142, 6, v152
	v_mov_b32_e32 v143, v142
	v_lshl_add_u32 v144, v151, 6, v153
	v_lshl_add_u32 v144, v144, 6, v152
	v_mov_b32_e32 v145, v144
	v_mov_b32_e32 v146, v144
	v_mov_b32_e32 v147, v144
	v_readfirstlane_b32 s42, v151
	s_lshl_b32 s43, s42, 12
	s_lshl_b32 s42, s42, 11
	s_add_u32 s43, s43, 0x2000
	v_bfe_u32 v152, v149, 2, 2
	v_lshrrev_b32_e32 v153, 1, v152
	v_xor_b32_e32 v152, v152, v153
	v_and_b32_e32 v152, 1, v152
	v_lshl_or_b32 v152, v152, 1, v153
	v_lshrrev_b32_e32 v153, 4, v149
	v_xor_b32_e32 v152, v152, v153
	v_lshlrev_b32_e32 v152, 4, v152
	v_and_b32_e32 v149, 15, v149
	v_lshl_add_u32 v149, v149, 6, v152
	v_lshrrev_b32_e32 v152, 1, v151
	v_and_b32_e32 v153, 1, v151
	v_lshl_add_u32 v138, v152, 12, v149
	v_lshl_add_u32 v140, v153, 12, v149
	v_add_u32_e32 v140, 0x2000, v140
	s_barrier
	v_mov_b32_e32 v2, 0
	v_mov_b32_e32 v3, 0
	v_mov_b32_e32 v4, 0
	v_mov_b32_e32 v5, 0
	v_mov_b32_e32 v6, 0
	v_mov_b32_e32 v7, 0
	v_mov_b32_e32 v8, 0
	v_mov_b32_e32 v9, 0
	v_mov_b32_e32 v10, 0
	v_mov_b32_e32 v11, 0
	v_mov_b32_e32 v12, 0
	v_mov_b32_e32 v13, 0
	v_mov_b32_e32 v14, 0
	v_mov_b32_e32 v15, 0
	v_mov_b32_e32 v16, 0
	v_mov_b32_e32 v17, 0
	v_mov_b32_e32 v18, 0
	v_mov_b32_e32 v19, 0
	v_mov_b32_e32 v20, 0
	v_mov_b32_e32 v21, 0
	v_mov_b32_e32 v22, 0
	v_mov_b32_e32 v23, 0
	v_mov_b32_e32 v24, 0
	v_mov_b32_e32 v25, 0
	v_mov_b32_e32 v26, 0
	v_mov_b32_e32 v27, 0
	v_mov_b32_e32 v28, 0
	v_mov_b32_e32 v29, 0
	v_mov_b32_e32 v30, 0
	v_mov_b32_e32 v31, 0
	v_mov_b32_e32 v32, 0
	v_mov_b32_e32 v33, 0
	v_mov_b32_e32 v34, 0
	v_mov_b32_e32 v35, 0
	v_mov_b32_e32 v36, 0
	v_mov_b32_e32 v37, 0
	v_mov_b32_e32 v38, 0
	v_mov_b32_e32 v39, 0
	v_mov_b32_e32 v40, 0
	v_mov_b32_e32 v41, 0
	v_mov_b32_e32 v42, 0
	v_mov_b32_e32 v43, 0
	v_mov_b32_e32 v44, 0
	v_mov_b32_e32 v45, 0
	v_mov_b32_e32 v46, 0
	v_mov_b32_e32 v47, 0
	v_mov_b32_e32 v48, 0
	v_mov_b32_e32 v49, 0
	v_mov_b32_e32 v50, 0
	v_mov_b32_e32 v51, 0
	v_mov_b32_e32 v52, 0
	v_mov_b32_e32 v53, 0
	v_mov_b32_e32 v54, 0
	v_mov_b32_e32 v55, 0
	v_mov_b32_e32 v56, 0
	v_mov_b32_e32 v57, 0
	v_mov_b32_e32 v58, 0
	v_mov_b32_e32 v59, 0
	v_mov_b32_e32 v60, 0
	v_mov_b32_e32 v61, 0
	v_mov_b32_e32 v62, 0
	v_mov_b32_e32 v63, 0
	v_mov_b32_e32 v64, 0
	v_mov_b32_e32 v65, 0
	v_mov_b32_e32 v74, 0
	v_mov_b32_e32 v75, 0
	v_mov_b32_e32 v76, 0
	v_mov_b32_e32 v77, 0
	v_mov_b32_e32 v78, 0
	v_mov_b32_e32 v79, 0
	v_mov_b32_e32 v80, 0
	v_mov_b32_e32 v81, 0
	v_mov_b32_e32 v82, 0
	v_mov_b32_e32 v83, 0
	v_mov_b32_e32 v84, 0
	v_mov_b32_e32 v85, 0
	v_mov_b32_e32 v86, 0
	v_mov_b32_e32 v87, 0
	v_mov_b32_e32 v88, 0
	v_mov_b32_e32 v89, 0
	v_mov_b32_e32 v90, 0
	v_mov_b32_e32 v91, 0
	v_mov_b32_e32 v92, 0
	v_mov_b32_e32 v93, 0
	v_mov_b32_e32 v94, 0
	v_mov_b32_e32 v95, 0
	v_mov_b32_e32 v96, 0
	v_mov_b32_e32 v97, 0
	v_mov_b32_e32 v98, 0
	v_mov_b32_e32 v99, 0
	v_mov_b32_e32 v100, 0
	v_mov_b32_e32 v101, 0
	v_mov_b32_e32 v102, 0
	v_mov_b32_e32 v103, 0
	v_mov_b32_e32 v104, 0
	v_mov_b32_e32 v105, 0
	v_mov_b32_e32 v106, 0
	v_mov_b32_e32 v107, 0
	v_mov_b32_e32 v108, 0
	v_mov_b32_e32 v109, 0
	v_mov_b32_e32 v110, 0
	v_mov_b32_e32 v111, 0
	v_mov_b32_e32 v112, 0
	v_mov_b32_e32 v113, 0
	v_mov_b32_e32 v114, 0
	v_mov_b32_e32 v115, 0
	v_mov_b32_e32 v116, 0
	v_mov_b32_e32 v117, 0
	v_mov_b32_e32 v118, 0
	v_mov_b32_e32 v119, 0
	v_mov_b32_e32 v120, 0
	v_mov_b32_e32 v121, 0
	v_mov_b32_e32 v122, 0
	v_mov_b32_e32 v123, 0
	v_mov_b32_e32 v124, 0
	v_mov_b32_e32 v125, 0
	v_mov_b32_e32 v126, 0
	v_mov_b32_e32 v127, 0
	v_mov_b32_e32 v128, 0
	v_mov_b32_e32 v129, 0
	v_mov_b32_e32 v130, 0
	v_mov_b32_e32 v131, 0
	v_mov_b32_e32 v132, 0
	v_mov_b32_e32 v133, 0
	v_mov_b32_e32 v134, 0
	v_mov_b32_e32 v135, 0
	v_mov_b32_e32 v136, 0
	v_mov_b32_e32 v137, 0
	s_add_u32 m0, s42, 0x0
	s_nop 0
	global_load_lds_dwordx4 v142, s[28:29]
	global_load_lds_dwordx4 v143, s[28:29] offset:1024
	s_add_u32 m0, s43, 0x0
	s_nop 0
	global_load_lds_dwordx4 v144, s[30:31]
	global_load_lds_dwordx4 v145, s[30:31] offset:1024
	global_load_lds_dwordx4 v146, s[30:31] offset:2048
	global_load_lds_dwordx4 v147, s[30:31] offset:3072
	s_add_u32 m0, s42, 0x6000
	s_add_u32 s28, s28, 0x100000
	s_addc_u32 s29, s29, 0
	global_load_lds_dwordx4 v142, s[28:29]
	global_load_lds_dwordx4 v143, s[28:29] offset:1024
	s_add_u32 m0, s43, 0x6000
	s_add_u32 s30, s30, 0x40000
	s_addc_u32 s31, s31, 0
	global_load_lds_dwordx4 v144, s[30:31]
	global_load_lds_dwordx4 v145, s[30:31] offset:1024
	global_load_lds_dwordx4 v146, s[30:31] offset:2048
	global_load_lds_dwordx4 v147, s[30:31] offset:3072
	s_mov_b32 s46, 10
	.p2align 6

; DI int TID() { int t = (int)__builtin_amdgcn_workitem_id_x(); asm volatile("" : "+v"(t)); return t; }
; #define BLOAD(A_, B_, kt) do { _Pragma("unroll") for (int i = 0; i < 4; ++i) { \
;     A_[i] = *(const u32x4*)((const char*)Ap + (aoff + (unsigned)(32 * i * lda + (kt) * 64) * 2u)); B_[i] = *(const u32x4*)((const char*)Wt + (woff + (unsigned)(32 * i * K + (kt) * 64) * 2u)); } } while (0)
; #define BLOAD(A_, B_, kt) do { _Pragma("unroll") for (int i = 0; i < 4; ++i) { \
;     A_[i] = *(const u32x4*)((const char*)Ap + (aoff + (unsigned)(32 * i * lda + (kt) * 64) * 2u)); B_[i] = *(const u32x4*)((const char*)Wt + (woff + (unsigned)(32 * i * K + (kt) * 64) * 2u)); } } while (0)
; #define BSTORE(A_, B_, buf) do { _Pragma("unroll") for (int i = 0; i < 4; ++i) { \
;     *(u32x4*)&As[(buf) * GBUF + (srow + 32 * i) * LDT + sc8] = A_[i]; \
;     *(u32x4*)&Bs[(buf) * GBUF + (srow + 32 * i) * LDT + sc8] = B_[i]; } } while (0)
; template <int NK>
; DI void gemm_run(PF& pf, const u16* __restrict__ Ap, int lda, const u16* __restrict__ Wt, f32x16 (&acc)[2][2], char* smem) {
;   constexpr int K = NK * 64;
;   const int tid = TID(), lane = tid & 63, w = tid >> 6, wm = w >> 1, wn = w & 1, r32 = lane & 31, hi = lane >> 5;
;   u16* As = (u16*)smem; u16* Bs = As + 128 * LDT;
;   const int srow = tid >> 3, sc8 = (tid & 7) * 8;
;   constexpr int nk = NK;
;   const unsigned aoff = (unsigned)(srow * lda + sc8) * 2u, woff = (unsigned)(srow * K + sc8) * 2u;
;     ...
;   __builtin_amdgcn_s_setprio(0);
;   __syncthreads();
;   BSTORE(pf.a0, pf.b0, 0);
;   BLOAD(pf.a0, pf.b0, 2);
;   __syncthreads();
; DI void tile_outproj(const Params& p, int l, const Chunk& ck, int tile, int next, PF& pf, char* smem) {
;   float* Cs = (float*)smem;
;   const int tid = TID(); const int mi = tile & (MTN - 1), ni = tile >> MTS; const int m0 = mi * 128, n0 = ni * 128;
;   f32x16 acc[2][2]; zero_acc(acc);
;   { const u16* Ap; const u16* Wt; outproj_ptrs(p, l, tile, Ap, Wt); gemm_run<16>(pf, Ap, 1024, Wt, acc, smem); }
.LBB1_255:
	s_add_i32 s41, s35, s78
	s_cmpk_gt_i32 s41, 0x1ff
	s_cselect_b64 s[24:25], -1, 0
	s_cmpk_lt_i32 s41, 0x200
	s_cselect_b32 s0, s41, -1
	s_and_b32 s27, s34, 0xfe0000
	s_and_b32 s26, s35, 0xffffff80
	s_lshl_b32 s26, s26, 1
	s_lshr_b32 s27, s27, 4
	s_add_u32 s28, s16, s27
	v_mov_b32_e32 v0, v172
	s_addc_u32 s29, s17, 0
	s_ashr_i32 s27, s26, 31
	s_lshl_b64 s[30:31], s[26:27], 6
	s_add_u32 s30, s36, s30
	s_addc_u32 s31, s37, s31
	s_setprio 0
	s_waitcnt lgkmcnt(0)
	v_and_b32_e32 v150, 63, v172
	v_lshrrev_b32_e32 v151, 6, v172
	v_bfe_u32 v152, v150, 4, 2
	v_lshrrev_b32_e32 v153, 1, v152
	v_xor_b32_e32 v152, v152, v153
	v_and_b32_e32 v152, 1, v152
	v_lshl_or_b32 v152, v152, 1, v153
	v_xor_b32_e32 v152, v152, v150
	v_and_b32_e32 v152, 3, v152
	v_lshlrev_b32_e32 v152, 4, v152
	v_lshrrev_b32_e32 v153, 2, v150
	v_lshl_add_u32 v143, v151, 5, v153
	v_lshl_add_u32 v143, v143, 6, v152
	v_mov_b32_e32 v144, v143
	v_lshl_add_u32 v145, v151, 6, v153
	v_lshl_add_u32 v145, v145, 6, v152
	v_mov_b32_e32 v146, v145
	v_mov_b32_e32 v147, v145
	v_mov_b32_e32 v148, v145
	v_readfirstlane_b32 s42, v151
	s_lshl_b32 s43, s42, 12
	s_lshl_b32 s42, s42, 11
	s_add_u32 s43, s43, 0x2000
	v_bfe_u32 v152, v150, 2, 2
	v_lshrrev_b32_e32 v153, 1, v152
	v_xor_b32_e32 v152, v152, v153
	v_and_b32_e32 v152, 1, v152
	v_lshl_or_b32 v152, v152, 1, v153
	v_lshrrev_b32_e32 v153, 4, v150
	v_xor_b32_e32 v152, v152, v153
	v_lshlrev_b32_e32 v152, 4, v152
	v_and_b32_e32 v150, 15, v150
	v_lshl_add_u32 v150, v150, 6, v152
	v_lshrrev_b32_e32 v152, 1, v151
	v_and_b32_e32 v153, 1, v151
	v_lshl_add_u32 v126, v152, 12, v150
	v_lshl_add_u32 v128, v153, 12, v150
	v_add_u32_e32 v128, 0x2000, v128
	s_barrier
	v_mov_b32_e32 v2, 0
	v_mov_b32_e32 v3, 0
	v_mov_b32_e32 v4, 0
	v_mov_b32_e32 v5, 0
	v_mov_b32_e32 v6, 0
	v_mov_b32_e32 v7, 0
	v_mov_b32_e32 v8, 0
	v_mov_b32_e32 v9, 0
	v_mov_b32_e32 v10, 0
	v_mov_b32_e32 v11, 0
	v_mov_b32_e32 v12, 0
	v_mov_b32_e32 v13, 0
	v_mov_b32_e32 v14, 0
	v_mov_b32_e32 v15, 0
	v_mov_b32_e32 v16, 0
	v_mov_b32_e32 v17, 0
	v_mov_b32_e32 v18, 0
	v_mov_b32_e32 v19, 0
	v_mov_b32_e32 v20, 0
	v_mov_b32_e32 v21, 0
	v_mov_b32_e32 v22, 0
	v_mov_b32_e32 v23, 0
	v_mov_b32_e32 v24, 0
	v_mov_b32_e32 v25, 0
	v_mov_b32_e32 v26, 0
	v_mov_b32_e32 v27, 0
	v_mov_b32_e32 v28, 0
	v_mov_b32_e32 v29, 0
	v_mov_b32_e32 v30, 0
	v_mov_b32_e32 v31, 0
	v_mov_b32_e32 v32, 0
	v_mov_b32_e32 v33, 0
	v_mov_b32_e32 v34, 0
	v_mov_b32_e32 v35, 0
	v_mov_b32_e32 v36, 0
	v_mov_b32_e32 v37, 0
	v_mov_b32_e32 v38, 0
	v_mov_b32_e32 v39, 0
	v_mov_b32_e32 v40, 0
	v_mov_b32_e32 v41, 0
	v_mov_b32_e32 v42, 0
	v_mov_b32_e32 v43, 0
	v_mov_b32_e32 v44, 0
	v_mov_b32_e32 v45, 0
	v_mov_b32_e32 v46, 0
	v_mov_b32_e32 v47, 0
	v_mov_b32_e32 v48, 0
	v_mov_b32_e32 v49, 0
	v_mov_b32_e32 v50, 0
	v_mov_b32_e32 v51, 0
	v_mov_b32_e32 v52, 0
	v_mov_b32_e32 v53, 0
	v_mov_b32_e32 v54, 0
	v_mov_b32_e32 v55, 0
	v_mov_b32_e32 v56, 0
	v_mov_b32_e32 v57, 0
	v_mov_b32_e32 v58, 0
	v_mov_b32_e32 v59, 0
	v_mov_b32_e32 v60, 0
	v_mov_b32_e32 v61, 0
	v_mov_b32_e32 v62, 0
	v_mov_b32_e32 v63, 0
	v_mov_b32_e32 v64, 0
	v_mov_b32_e32 v65, 0
	v_mov_b32_e32 v74, 0
	v_mov_b32_e32 v75, 0
	v_mov_b32_e32 v76, 0
	v_mov_b32_e32 v77, 0
	v_mov_b32_e32 v78, 0
	v_mov_b32_e32 v79, 0
	v_mov_b32_e32 v80, 0
	v_mov_b32_e32 v81, 0
	v_mov_b32_e32 v82, 0
	v_mov_b32_e32 v83, 0
	v_mov_b32_e32 v84, 0
	v_mov_b32_e32 v85, 0
	v_mov_b32_e32 v86, 0
	v_mov_b32_e32 v87, 0
	v_mov_b32_e32 v88, 0
	v_mov_b32_e32 v89, 0
	v_mov_b32_e32 v90, 0
	v_mov_b32_e32 v91, 0
	v_mov_b32_e32 v92, 0
	v_mov_b32_e32 v93, 0
	v_mov_b32_e32 v94, 0
	v_mov_b32_e32 v95, 0
	v_mov_b32_e32 v96, 0
	v_mov_b32_e32 v97, 0
	v_mov_b32_e32 v98, 0
	v_mov_b32_e32 v99, 0
	v_mov_b32_e32 v100, 0
	v_mov_b32_e32 v101, 0
	v_mov_b32_e32 v102, 0
	v_mov_b32_e32 v103, 0
	v_mov_b32_e32 v104, 0
	v_mov_b32_e32 v105, 0
	v_mov_b32_e32 v106, 0
	v_mov_b32_e32 v107, 0
	v_mov_b32_e32 v108, 0
	v_mov_b32_e32 v109, 0
	v_mov_b32_e32 v110, 0
	v_mov_b32_e32 v111, 0
	v_mov_b32_e32 v112, 0
	v_mov_b32_e32 v113, 0
	v_mov_b32_e32 v114, 0
	v_mov_b32_e32 v115, 0
	v_mov_b32_e32 v116, 0
	v_mov_b32_e32 v117, 0
	v_mov_b32_e32 v118, 0
	v_mov_b32_e32 v119, 0
	v_mov_b32_e32 v120, 0
	v_mov_b32_e32 v121, 0
	v_mov_b32_e32 v208, 0
	v_mov_b32_e32 v209, 0
	v_mov_b32_e32 v210, 0
	v_mov_b32_e32 v211, 0
	v_mov_b32_e32 v212, 0
	v_mov_b32_e32 v213, 0
	v_mov_b32_e32 v214, 0
	v_mov_b32_e32 v215, 0
	v_mov_b32_e32 v216, 0
	v_mov_b32_e32 v217, 0
	v_mov_b32_e32 v218, 0
	v_mov_b32_e32 v219, 0
	v_mov_b32_e32 v220, 0
	v_mov_b32_e32 v221, 0
	v_mov_b32_e32 v222, 0
	v_mov_b32_e32 v223, 0
	s_add_u32 m0, s42, 0x0
	s_nop 0
	global_load_lds_dwordx4 v143, s[28:29]
	global_load_lds_dwordx4 v144, s[28:29] offset:1024
	s_add_u32 m0, s43, 0x0
	s_nop 0
	global_load_lds_dwordx4 v145, s[30:31]
	global_load_lds_dwordx4 v146, s[30:31] offset:1024
	global_load_lds_dwordx4 v147, s[30:31] offset:2048
	global_load_lds_dwordx4 v148, s[30:31] offset:3072
	s_add_u32 m0, s42, 0x6000
	s_add_u32 s28, s28, 0x100000
	s_addc_u32 s29, s29, 0
	global_load_lds_dwordx4 v143, s[28:29]
	global_load_lds_dwordx4 v144, s[28:29] offset:1024
	s_add_u32 m0, s43, 0x6000
	s_add_u32 s30, s30, 0x10000
	s_addc_u32 s31, s31, 0
	global_load_lds_dwordx4 v145, s[30:31]
	global_load_lds_dwordx4 v146, s[30:31] offset:1024
	global_load_lds_dwordx4 v147, s[30:31] offset:2048
	global_load_lds_dwordx4 v148, s[30:31] offset:3072
	s_mov_b32 s46, 10
	.p2align 6

; #define BLOAD(A_, B_, kt) do { _Pragma("unroll") for (int i = 0; i < 4; ++i) { \
;     A_[i] = *(const u32x4*)((const char*)Ap + (aoff + (unsigned)(32 * i * lda + (kt) * 64) * 2u)); B_[i] = *(const u32x4*)((const char*)Wt + (woff + (unsigned)(32 * i * K + (kt) * 64) * 2u)); } } while (0)
; #define BLOAD(A_, B_, kt) do { _Pragma("unroll") for (int i = 0; i < 4; ++i) { \
;     A_[i] = *(const u32x4*)((const char*)Ap + (aoff + (unsigned)(32 * i * lda + (kt) * 64) * 2u)); B_[i] = *(const u32x4*)((const char*)Wt + (woff + (unsigned)(32 * i * K + (kt) * 64) * 2u)); } } while (0)
; #define BSTORE(A_, B_, buf) do { _Pragma("unroll") for (int i = 0; i < 4; ++i) { \
;     *(u32x4*)&As[(buf) * GBUF + (srow + 32 * i) * LDT + sc8] = A_[i]; \
;     *(u32x4*)&Bs[(buf) * GBUF + (srow + 32 * i) * LDT + sc8] = B_[i]; } } while (0)
; template <bool ROWNORM, int NK>
; DI void gemm_main_bf(const u16* __restrict__ Ap, int lda, const u16* __restrict__ Wt, f32x16 (&acc)[2][2], char* smem, float* rinv_s) {
;     ...
;   __builtin_amdgcn_s_setprio(0);
;   BLOAD(a0, b0, 0); BLOAD(a1, b1, 1);
;   __syncthreads();
;   BSTORE(a0, b0, 0);
;   BLOAD(a0, b0, 2);
;   __syncthreads();
; #pragma unroll
;   for (int kt = 0; kt < nk; kt += 2) {
;     BCOMP(0);
;     BSTORE(a1, b1, 1);
;     if (kt + 3 < nk) BLOAD(a1, b1, kt + 3);
;     __syncthreads();
;     BCOMP(1);
;     if (kt + 2 < nk) { BSTORE(a0, b0, 0); if (kt + 4 < nk) BLOAD(a0, b0, kt + 4); }
;     __syncthreads();
;   }
; DI void tile_branch(const Params& p, int l, int tile, char* smem) {
;     ...
;   for (int br = 0; br < 3; ++br) {
;     unsigned gpk[2][2][8];
;     {
;       f32x16 accg[2][2]; zero_acc(accg);
;       gemm_main_bf<false, 16>((const u16*)(p.ws + OFF_XB) + (size_t)m0 * 1024, 1024,
;                               (const u16*)(p.ws + OFF_WIN + l * SZ_WIN) + (size_t)(5760 + br * 1024 + n0) * 1024, accg, smem, nullptr);
.Lbr_loop:
	v_mov_b32_e32 v2, 0
	v_mov_b32_e32 v3, 0
	v_mov_b32_e32 v4, 0
	v_mov_b32_e32 v5, 0
	v_mov_b32_e32 v6, 0
	v_mov_b32_e32 v7, 0
	v_mov_b32_e32 v8, 0
	v_mov_b32_e32 v9, 0
	v_mov_b32_e32 v10, 0
	v_mov_b32_e32 v11, 0
	v_mov_b32_e32 v12, 0
	v_mov_b32_e32 v13, 0
	v_mov_b32_e32 v14, 0
	v_mov_b32_e32 v15, 0
	v_mov_b32_e32 v16, 0
	v_mov_b32_e32 v17, 0
	v_mov_b32_e32 v18, 0
	v_mov_b32_e32 v19, 0
	v_mov_b32_e32 v20, 0
	v_mov_b32_e32 v21, 0
	v_mov_b32_e32 v22, 0
	v_mov_b32_e32 v23, 0
	v_mov_b32_e32 v24, 0
	v_mov_b32_e32 v25, 0
	v_mov_b32_e32 v26, 0
	v_mov_b32_e32 v27, 0
	v_mov_b32_e32 v28, 0
	v_mov_b32_e32 v29, 0
	v_mov_b32_e32 v30, 0
	v_mov_b32_e32 v31, 0
	v_mov_b32_e32 v32, 0
	v_mov_b32_e32 v33, 0
	v_mov_b32_e32 v34, 0
	v_mov_b32_e32 v35, 0
	v_mov_b32_e32 v36, 0
	v_mov_b32_e32 v37, 0
	v_mov_b32_e32 v38, 0
	v_mov_b32_e32 v39, 0
	v_mov_b32_e32 v40, 0
	v_mov_b32_e32 v41, 0
	v_mov_b32_e32 v42, 0
	v_mov_b32_e32 v43, 0
	v_mov_b32_e32 v44, 0
	v_mov_b32_e32 v45, 0
	v_mov_b32_e32 v46, 0
	v_mov_b32_e32 v47, 0
	v_mov_b32_e32 v48, 0
	v_mov_b32_e32 v49, 0
	v_mov_b32_e32 v50, 0
	v_mov_b32_e32 v51, 0
	v_mov_b32_e32 v52, 0
	v_mov_b32_e32 v53, 0
	v_mov_b32_e32 v54, 0
	v_mov_b32_e32 v55, 0
	v_mov_b32_e32 v56, 0
	v_mov_b32_e32 v57, 0
	v_mov_b32_e32 v58, 0
	v_mov_b32_e32 v59, 0
	v_mov_b32_e32 v60, 0
	v_mov_b32_e32 v61, 0
	v_mov_b32_e32 v62, 0
	v_mov_b32_e32 v63, 0
	v_mov_b32_e32 v64, 0
	v_mov_b32_e32 v65, 0
	s_mov_b32 s74, 7
	.p2align 6
.Lbr_gate_k:
	s_waitcnt vmcnt(8)
	s_barrier
	ds_read_b128 v[208:211], v240 offset:0
	ds_read_b128 v[224:227], v241 offset:0
	ds_read_b128 v[228:231], v241 offset:1024
	ds_read_b128 v[232:235], v241 offset:2048
	ds_read_b128 v[236:239], v241 offset:3072
	s_add_u32 m0, s52, 0xc000
	s_add_u32 s28, s28, 0x100000
	s_addc_u32 s29, s29, 0
	global_load_lds_dwordx4 v251, s[28:29]
	global_load_lds_dwordx4 v251, s[28:29] offset:1024
	s_add_u32 m0, s53, 0xc000
	s_add_u32 s30, s30, 0x30000
	s_addc_u32 s31, s31, 0
	global_load_lds_dwordx4 v251, s[30:31]
	global_load_lds_dwordx4 v251, s[30:31] offset:1024
	ds_read_b128 v[212:215], v240 offset:1024
	ds_read_b128 v[216:219], v240 offset:2048
	ds_read_b128 v[220:223], v240 offset:3072
	s_waitcnt lgkmcnt(6)
	v_mfma_f32_16x16x32_bf16 v[2:5], v[224:227], v[208:211], v[2:5]
	s_waitcnt lgkmcnt(5)
	v_mfma_f32_16x16x32_bf16 v[6:9], v[228:231], v[208:211], v[6:9]
	s_waitcnt lgkmcnt(4)
	v_mfma_f32_16x16x32_bf16 v[10:13], v[232:235], v[208:211], v[10:13]
	s_waitcnt lgkmcnt(3)
	v_mfma_f32_16x16x32_bf16 v[14:17], v[236:239], v[208:211], v[14:17]
	s_waitcnt lgkmcnt(2)
	v_mfma_f32_16x16x32_bf16 v[18:21], v[224:227], v[212:215], v[18:21]
	v_mfma_f32_16x16x32_bf16 v[22:25], v[228:231], v[212:215], v[22:25]
	v_mfma_f32_16x16x32_bf16 v[26:29], v[232:235], v[212:215], v[26:29]
	v_mfma_f32_16x16x32_bf16 v[30:33], v[236:239], v[212:215], v[30:33]
	s_waitcnt lgkmcnt(1)
	v_mfma_f32_16x16x32_bf16 v[34:37], v[224:227], v[216:219], v[34:37]
	v_mfma_f32_16x16x32_bf16 v[38:41], v[228:231], v[216:219], v[38:41]
	v_mfma_f32_16x16x32_bf16 v[42:45], v[232:235], v[216:219], v[42:45]
	v_mfma_f32_16x16x32_bf16 v[46:49], v[236:239], v[216:219], v[46:49]
	s_waitcnt lgkmcnt(0)
	v_mfma_f32_16x16x32_bf16 v[50:53], v[224:227], v[220:223], v[50:53]
	v_mfma_f32_16x16x32_bf16 v[54:57], v[228:231], v[220:223], v[54:57]
	v_mfma_f32_16x16x32_bf16 v[58:61], v[232:235], v[220:223], v[58:61]
	v_mfma_f32_16x16x32_bf16 v[62:65], v[236:239], v[220:223], v[62:65]
	s_waitcnt vmcnt(8)
	s_barrier
	ds_read_b128 v[208:211], v240 offset:16384
	ds_read_b128 v[224:227], v241 offset:16384
	ds_read_b128 v[228:231], v241 offset:17408
	ds_read_b128 v[232:235], v241 offset:18432
	ds_read_b128 v[236:239], v241 offset:19456
	s_add_u32 m0, s52, 0x0
	s_add_u32 s28, s28, 0x100000
	s_addc_u32 s29, s29, 0
	global_load_lds_dwordx4 v251, s[28:29]
	global_load_lds_dwordx4 v251, s[28:29] offset:1024
	s_add_u32 m0, s53, 0x0
	s_add_u32 s30, s30, 0x30000
	s_addc_u32 s31, s31, 0
	global_load_lds_dwordx4 v251, s[30:31]
	global_load_lds_dwordx4 v251, s[30:31] offset:1024
	ds_read_b128 v[212:215], v240 offset:17408
	ds_read_b128 v[216:219], v240 offset:18432
	ds_read_b128 v[220:223], v240 offset:19456
	s_waitcnt lgkmcnt(6)
	v_mfma_f32_16x16x32_bf16 v[2:5], v[224:227], v[208:211], v[2:5]
	s_waitcnt lgkmcnt(5)
	v_mfma_f32_16x16x32_bf16 v[6:9], v[228:231], v[208:211], v[6:9]
	s_waitcnt lgkmcnt(4)
	v_mfma_f32_16x16x32_bf16 v[10:13], v[232:235], v[208:211], v[10:13]
	s_waitcnt lgkmcnt(3)
	v_mfma_f32_16x16x32_bf16 v[14:17], v[236:239], v[208:211], v[14:17]
	s_waitcnt lgkmcnt(2)
	v_mfma_f32_16x16x32_bf16 v[18:21], v[224:227], v[212:215], v[18:21]
	v_mfma_f32_16x16x32_bf16 v[22:25], v[228:231], v[212:215], v[22:25]
	v_mfma_f32_16x16x32_bf16 v[26:29], v[232:235], v[212:215], v[26:29]
	v_mfma_f32_16x16x32_bf16 v[30:33], v[236:239], v[212:215], v[30:33]
	s_waitcnt lgkmcnt(1)
	v_mfma_f32_16x16x32_bf16 v[34:37], v[224:227], v[216:219], v[34:37]
	v_mfma_f32_16x16x32_bf16 v[38:41], v[228:231], v[216:219], v[38:41]
	v_mfma_f32_16x16x32_bf16 v[42:45], v[232:235], v[216:219], v[42:45]
	v_mfma_f32_16x16x32_bf16 v[46:49], v[236:239], v[216:219], v[46:49]
	s_waitcnt lgkmcnt(0)
	v_mfma_f32_16x16x32_bf16 v[50:53], v[224:227], v[220:223], v[50:53]
	v_mfma_f32_16x16x32_bf16 v[54:57], v[228:231], v[220:223], v[54:57]
	v_mfma_f32_16x16x32_bf16 v[58:61], v[232:235], v[220:223], v[58:61]
	v_mfma_f32_16x16x32_bf16 v[62:65], v[236:239], v[220:223], v[62:65]
	s_waitcnt vmcnt(8)
	s_barrier
; #define BLOAD(A_, B_, kt) do { _Pragma("unroll") for (int i = 0; i < 4; ++i) { \
;     A_[i] = *(const u32x4*)((const char*)Ap + (aoff + (unsigned)(32 * i * lda + (kt) * 64) * 2u)); B_[i] = *(const u32x4*)((const char*)Wt + (woff + (unsigned)(32 * i * K + (kt) * 64) * 2u)); } } while (0)
; #define BLOAD(A_, B_, kt) do { _Pragma("unroll") for (int i = 0; i < 4; ++i) { \
;     A_[i] = *(const u32x4*)((const char*)Ap + (aoff + (unsigned)(32 * i * lda + (kt) * 64) * 2u)); B_[i] = *(const u32x4*)((const char*)Wt + (woff + (unsigned)(32 * i * K + (kt) * 64) * 2u)); } } while (0)
; #define BSTORE(A_, B_, buf) do { _Pragma("unroll") for (int i = 0; i < 4; ++i) { \
;     *(u32x4*)&As[(buf) * GBUF + (srow + 32 * i) * LDT + sc8] = A_[i]; \
;     *(u32x4*)&Bs[(buf) * GBUF + (srow + 32 * i) * LDT + sc8] = B_[i]; } } while (0)
; template <bool ROWNORM, int NK>
; DI void gemm_main_bf(const u16* __restrict__ Ap, int lda, const u16* __restrict__ Wt, f32x16 (&acc)[2][2], char* smem, float* rinv_s) {
;     ...
;   __builtin_amdgcn_s_setprio(0);
;   BLOAD(a0, b0, 0); BLOAD(a1, b1, 1);
;   __syncthreads();
;   BSTORE(a0, b0, 0);
;   BLOAD(a0, b0, 2);
;   __syncthreads();
; #pragma unroll
;   for (int kt = 0; kt < nk; kt += 2) {
;     BCOMP(0);
;     BSTORE(a1, b1, 1);
;     if (kt + 3 < nk) BLOAD(a1, b1, kt + 3);
;     __syncthreads();
;     BCOMP(1);
;     if (kt + 2 < nk) { BSTORE(a0, b0, 0); if (kt + 4 < nk) BLOAD(a0, b0, kt + 4); }
;     __syncthreads();
;   }
	ds_read_b128 v[208:211], v240 offset:32768
	ds_read_b128 v[224:227], v241 offset:32768
	ds_read_b128 v[228:231], v241 offset:33792
	ds_read_b128 v[232:235], v241 offset:34816
	ds_read_b128 v[236:239], v241 offset:35840
	s_add_u32 m0, s52, 0x4000
	s_add_u32 s28, s28, 0x100000
	s_addc_u32 s29, s29, 0
	global_load_lds_dwordx4 v251, s[28:29]
	global_load_lds_dwordx4 v251, s[28:29] offset:1024
	s_add_u32 m0, s53, 0x4000
	s_add_u32 s30, s30, 0x30000
	s_addc_u32 s31, s31, 0
	global_load_lds_dwordx4 v251, s[30:31]
	global_load_lds_dwordx4 v251, s[30:31] offset:1024
	ds_read_b128 v[212:215], v240 offset:33792
	ds_read_b128 v[216:219], v240 offset:34816
	ds_read_b128 v[220:223], v240 offset:35840
	s_waitcnt lgkmcnt(6)
	v_mfma_f32_16x16x32_bf16 v[2:5], v[224:227], v[208:211], v[2:5]
	s_waitcnt lgkmcnt(5)
	v_mfma_f32_16x16x32_bf16 v[6:9], v[228:231], v[208:211], v[6:9]
	s_waitcnt lgkmcnt(4)
	v_mfma_f32_16x16x32_bf16 v[10:13], v[232:235], v[208:211], v[10:13]
	s_waitcnt lgkmcnt(3)
	v_mfma_f32_16x16x32_bf16 v[14:17], v[236:239], v[208:211], v[14:17]
	s_waitcnt lgkmcnt(2)
	v_mfma_f32_16x16x32_bf16 v[18:21], v[224:227], v[212:215], v[18:21]
	v_mfma_f32_16x16x32_bf16 v[22:25], v[228:231], v[212:215], v[22:25]
	v_mfma_f32_16x16x32_bf16 v[26:29], v[232:235], v[212:215], v[26:29]
	v_mfma_f32_16x16x32_bf16 v[30:33], v[236:239], v[212:215], v[30:33]
	s_waitcnt lgkmcnt(1)
	v_mfma_f32_16x16x32_bf16 v[34:37], v[224:227], v[216:219], v[34:37]
	v_mfma_f32_16x16x32_bf16 v[38:41], v[228:231], v[216:219], v[38:41]
	v_mfma_f32_16x16x32_bf16 v[42:45], v[232:235], v[216:219], v[42:45]
	v_mfma_f32_16x16x32_bf16 v[46:49], v[236:239], v[216:219], v[46:49]
	s_waitcnt lgkmcnt(0)
	v_mfma_f32_16x16x32_bf16 v[50:53], v[224:227], v[220:223], v[50:53]
	v_mfma_f32_16x16x32_bf16 v[54:57], v[228:231], v[220:223], v[54:57]
	v_mfma_f32_16x16x32_bf16 v[58:61], v[232:235], v[220:223], v[58:61]
	v_mfma_f32_16x16x32_bf16 v[62:65], v[236:239], v[220:223], v[62:65]
	s_waitcnt vmcnt(8)
	s_barrier
	ds_read_b128 v[208:211], v240 offset:49152
	ds_read_b128 v[224:227], v241 offset:49152
	ds_read_b128 v[228:231], v241 offset:50176
	ds_read_b128 v[232:235], v241 offset:51200
	ds_read_b128 v[236:239], v241 offset:52224
	s_add_u32 m0, s52, 0x8000
	s_add_u32 s28, s28, 0x100000
	s_addc_u32 s29, s29, 0
	global_load_lds_dwordx4 v251, s[28:29]
	global_load_lds_dwordx4 v251, s[28:29] offset:1024
	s_add_u32 m0, s53, 0x8000
	s_add_u32 s30, s30, 0x30000
	s_addc_u32 s31, s31, 0
	global_load_lds_dwordx4 v251, s[30:31]
	global_load_lds_dwordx4 v251, s[30:31] offset:1024
	ds_read_b128 v[212:215], v240 offset:50176
	ds_read_b128 v[216:219], v240 offset:51200
	ds_read_b128 v[220:223], v240 offset:52224
	s_waitcnt lgkmcnt(6)
	v_mfma_f32_16x16x32_bf16 v[2:5], v[224:227], v[208:211], v[2:5]
	s_waitcnt lgkmcnt(5)
	v_mfma_f32_16x16x32_bf16 v[6:9], v[228:231], v[208:211], v[6:9]
	s_waitcnt lgkmcnt(4)
	v_mfma_f32_16x16x32_bf16 v[10:13], v[232:235], v[208:211], v[10:13]
	s_waitcnt lgkmcnt(3)
	v_mfma_f32_16x16x32_bf16 v[14:17], v[236:239], v[208:211], v[14:17]
	s_waitcnt lgkmcnt(2)
	v_mfma_f32_16x16x32_bf16 v[18:21], v[224:227], v[212:215], v[18:21]
	v_mfma_f32_16x16x32_bf16 v[22:25], v[228:231], v[212:215], v[22:25]
	v_mfma_f32_16x16x32_bf16 v[26:29], v[232:235], v[212:215], v[26:29]
	v_mfma_f32_16x16x32_bf16 v[30:33], v[236:239], v[212:215], v[30:33]
	s_waitcnt lgkmcnt(1)
	v_mfma_f32_16x16x32_bf16 v[34:37], v[224:227], v[216:219], v[34:37]
	v_mfma_f32_16x16x32_bf16 v[38:41], v[228:231], v[216:219], v[38:41]
	v_mfma_f32_16x16x32_bf16 v[42:45], v[232:235], v[216:219], v[42:45]
	v_mfma_f32_16x16x32_bf16 v[46:49], v[236:239], v[216:219], v[46:49]
	s_waitcnt lgkmcnt(0)
	v_mfma_f32_16x16x32_bf16 v[50:53], v[224:227], v[220:223], v[50:53]
	v_mfma_f32_16x16x32_bf16 v[54:57], v[228:231], v[220:223], v[54:57]
	v_mfma_f32_16x16x32_bf16 v[58:61], v[232:235], v[220:223], v[58:61]
	v_mfma_f32_16x16x32_bf16 v[62:65], v[236:239], v[220:223], v[62:65]
	s_sub_u32 s74, s74, 1
	s_cmp_lg_u32 s74, 0
	s_cbranch_scc1 .Lbr_gate_k
	s_waitcnt vmcnt(8)
	s_barrier
	ds_read_b128 v[208:211], v240 offset:0
	ds_read_b128 v[224:227], v241 offset:0
	ds_read_b128 v[228:231], v241 offset:1024
	ds_read_b128 v[232:235], v241 offset:2048
	ds_read_b128 v[236:239], v241 offset:3072
	s_add_u32 m0, s52, 0xc000
	s_add_u32 s28, s28, 0x100000
	s_addc_u32 s29, s29, 0
	global_load_lds_dwordx4 v251, s[28:29]
	global_load_lds_dwordx4 v251, s[28:29] offset:1024
	s_add_u32 m0, s53, 0xc000
	s_add_u32 s30, s30, 0x30000
	s_addc_u32 s31, s31, 0
	global_load_lds_dwordx4 v251, s[30:31]
	global_load_lds_dwordx4 v251, s[30:31] offset:1024
	ds_read_b128 v[212:215], v240 offset:1024
	ds_read_b128 v[216:219], v240 offset:2048
	ds_read_b128 v[220:223], v240 offset:3072
	s_waitcnt lgkmcnt(6)
	v_mfma_f32_16x16x32_bf16 v[2:5], v[224:227], v[208:211], v[2:5]
	s_waitcnt lgkmcnt(5)
	v_mfma_f32_16x16x32_bf16 v[6:9], v[228:231], v[208:211], v[6:9]
	s_waitcnt lgkmcnt(4)
	v_mfma_f32_16x16x32_bf16 v[10:13], v[232:235], v[208:211], v[10:13]
	s_waitcnt lgkmcnt(3)
	v_mfma_f32_16x16x32_bf16 v[14:17], v[236:239], v[208:211], v[14:17]
	s_waitcnt lgkmcnt(2)
	v_mfma_f32_16x16x32_bf16 v[18:21], v[224:227], v[212:215], v[18:21]
	v_mfma_f32_16x16x32_bf16 v[22:25], v[228:231], v[212:215], v[22:25]
	v_mfma_f32_16x16x32_bf16 v[26:29], v[232:235], v[212:215], v[26:29]
	v_mfma_f32_16x16x32_bf16 v[30:33], v[236:239], v[212:215], v[30:33]
	s_waitcnt lgkmcnt(1)
	v_mfma_f32_16x16x32_bf16 v[34:37], v[224:227], v[216:219], v[34:37]
	v_mfma_f32_16x16x32_bf16 v[38:41], v[228:231], v[216:219], v[38:41]
	v_mfma_f32_16x16x32_bf16 v[42:45], v[232:235], v[216:219], v[42:45]
	v_mfma_f32_16x16x32_bf16 v[46:49], v[236:239], v[216:219], v[46:49]
	s_waitcnt lgkmcnt(0)
	v_mfma_f32_16x16x32_bf16 v[50:53], v[224:227], v[220:223], v[50:53]
	v_mfma_f32_16x16x32_bf16 v[54:57], v[228:231], v[220:223], v[54:57]
	v_mfma_f32_16x16x32_bf16 v[58:61], v[232:235], v[220:223], v[58:61]
	v_mfma_f32_16x16x32_bf16 v[62:65], v[236:239], v[220:223], v[62:65]
	s_waitcnt vmcnt(8)
	s_barrier
; #define BLOAD(A_, B_, kt) do { _Pragma("unroll") for (int i = 0; i < 4; ++i) { \
;     A_[i] = *(const u32x4*)((const char*)Ap + (aoff + (unsigned)(32 * i * lda + (kt) * 64) * 2u)); B_[i] = *(const u32x4*)((const char*)Wt + (woff + (unsigned)(32 * i * K + (kt) * 64) * 2u)); } } while (0)
; #define BLOAD(A_, B_, kt) do { _Pragma("unroll") for (int i = 0; i < 4; ++i) { \
;     A_[i] = *(const u32x4*)((const char*)Ap + (aoff + (unsigned)(32 * i * lda + (kt) * 64) * 2u)); B_[i] = *(const u32x4*)((const char*)Wt + (woff + (unsigned)(32 * i * K + (kt) * 64) * 2u)); } } while (0)
; #define BSTORE(A_, B_, buf) do { _Pragma("unroll") for (int i = 0; i < 4; ++i) { \
;     *(u32x4*)&As[(buf) * GBUF + (srow + 32 * i) * LDT + sc8] = A_[i]; \
;     *(u32x4*)&Bs[(buf) * GBUF + (srow + 32 * i) * LDT + sc8] = B_[i]; } } while (0)
; template <bool ROWNORM, int NK>
; DI void gemm_main_bf(const u16* __restrict__ Ap, int lda, const u16* __restrict__ Wt, f32x16 (&acc)[2][2], char* smem, float* rinv_s) {
;     ...
; #pragma unroll
;   for (int kt = 0; kt < nk; kt += 2) {
;     BCOMP(0);
;     BSTORE(a1, b1, 1);
;     if (kt + 3 < nk) BLOAD(a1, b1, kt + 3);
;     __syncthreads();
;     BCOMP(1);
;     if (kt + 2 < nk) { BSTORE(a0, b0, 0); if (kt + 4 < nk) BLOAD(a0, b0, kt + 4); }
;     __syncthreads();
;   }
; DI void tile_branch(const Params& p, int l, int tile, char* smem) {
;     ...
;       __syncthreads();
; #pragma unroll
;       for (int mt = 0; mt < 2; ++mt)
; #pragma unroll
;         for (int g4 = 0; g4 < 4; ++g4) {
;           const f32x4 r4 = *(const f32x4*)&rinv_s[wm * 64 + mt * 32 + 8 * g4 + 4 * hi];
	ds_read_b128 v[208:211], v240 offset:16384
	ds_read_b128 v[224:227], v241 offset:16384
	ds_read_b128 v[228:231], v241 offset:17408
	ds_read_b128 v[232:235], v241 offset:18432
	ds_read_b128 v[236:239], v241 offset:19456
	ds_read_b128 v[212:215], v240 offset:17408
	ds_read_b128 v[216:219], v240 offset:18432
	ds_read_b128 v[220:223], v240 offset:19456
	s_waitcnt lgkmcnt(6)
	v_mfma_f32_16x16x32_bf16 v[2:5], v[224:227], v[208:211], v[2:5]
	s_waitcnt lgkmcnt(5)
	v_mfma_f32_16x16x32_bf16 v[6:9], v[228:231], v[208:211], v[6:9]
	s_waitcnt lgkmcnt(4)
	v_mfma_f32_16x16x32_bf16 v[10:13], v[232:235], v[208:211], v[10:13]
	s_waitcnt lgkmcnt(3)
	v_mfma_f32_16x16x32_bf16 v[14:17], v[236:239], v[208:211], v[14:17]
	s_waitcnt lgkmcnt(2)
	v_mfma_f32_16x16x32_bf16 v[18:21], v[224:227], v[212:215], v[18:21]
	v_mfma_f32_16x16x32_bf16 v[22:25], v[228:231], v[212:215], v[22:25]
	v_mfma_f32_16x16x32_bf16 v[26:29], v[232:235], v[212:215], v[26:29]
	v_mfma_f32_16x16x32_bf16 v[30:33], v[236:239], v[212:215], v[30:33]
	s_waitcnt lgkmcnt(1)
	v_mfma_f32_16x16x32_bf16 v[34:37], v[224:227], v[216:219], v[34:37]
	v_mfma_f32_16x16x32_bf16 v[38:41], v[228:231], v[216:219], v[38:41]
	v_mfma_f32_16x16x32_bf16 v[42:45], v[232:235], v[216:219], v[42:45]
	v_mfma_f32_16x16x32_bf16 v[46:49], v[236:239], v[216:219], v[46:49]
	s_waitcnt lgkmcnt(0)
	v_mfma_f32_16x16x32_bf16 v[50:53], v[224:227], v[220:223], v[50:53]
	v_mfma_f32_16x16x32_bf16 v[54:57], v[228:231], v[220:223], v[54:57]
	v_mfma_f32_16x16x32_bf16 v[58:61], v[232:235], v[220:223], v[58:61]
	v_mfma_f32_16x16x32_bf16 v[62:65], v[236:239], v[220:223], v[62:65]
	s_waitcnt vmcnt(4)
	s_barrier
	ds_read_b128 v[208:211], v240 offset:32768
	ds_read_b128 v[224:227], v241 offset:32768
	ds_read_b128 v[228:231], v241 offset:33792
	ds_read_b128 v[232:235], v241 offset:34816
	ds_read_b128 v[236:239], v241 offset:35840
	ds_read_b128 v[212:215], v240 offset:33792
	ds_read_b128 v[216:219], v240 offset:34816
	ds_read_b128 v[220:223], v240 offset:35840
	s_waitcnt lgkmcnt(6)
	v_mfma_f32_16x16x32_bf16 v[2:5], v[224:227], v[208:211], v[2:5]
	s_waitcnt lgkmcnt(5)
	v_mfma_f32_16x16x32_bf16 v[6:9], v[228:231], v[208:211], v[6:9]
	s_waitcnt lgkmcnt(4)
	v_mfma_f32_16x16x32_bf16 v[10:13], v[232:235], v[208:211], v[10:13]
	s_waitcnt lgkmcnt(3)
	v_mfma_f32_16x16x32_bf16 v[14:17], v[236:239], v[208:211], v[14:17]
	s_waitcnt lgkmcnt(2)
	v_mfma_f32_16x16x32_bf16 v[18:21], v[224:227], v[212:215], v[18:21]
	v_mfma_f32_16x16x32_bf16 v[22:25], v[228:231], v[212:215], v[22:25]
	v_mfma_f32_16x16x32_bf16 v[26:29], v[232:235], v[212:215], v[26:29]
	v_mfma_f32_16x16x32_bf16 v[30:33], v[236:239], v[212:215], v[30:33]
	s_waitcnt lgkmcnt(1)
	v_mfma_f32_16x16x32_bf16 v[34:37], v[224:227], v[216:219], v[34:37]
	v_mfma_f32_16x16x32_bf16 v[38:41], v[228:231], v[216:219], v[38:41]
	v_mfma_f32_16x16x32_bf16 v[42:45], v[232:235], v[216:219], v[42:45]
	v_mfma_f32_16x16x32_bf16 v[46:49], v[236:239], v[216:219], v[46:49]
	s_waitcnt lgkmcnt(0)
	v_mfma_f32_16x16x32_bf16 v[50:53], v[224:227], v[220:223], v[50:53]
	v_mfma_f32_16x16x32_bf16 v[54:57], v[228:231], v[220:223], v[54:57]
	v_mfma_f32_16x16x32_bf16 v[58:61], v[232:235], v[220:223], v[58:61]
	v_mfma_f32_16x16x32_bf16 v[62:65], v[236:239], v[220:223], v[62:65]
	s_waitcnt vmcnt(0)
	s_barrier
	ds_read_b128 v[208:211], v240 offset:49152
	ds_read_b128 v[224:227], v241 offset:49152
	ds_read_b128 v[228:231], v241 offset:50176
	ds_read_b128 v[232:235], v241 offset:51200
	ds_read_b128 v[236:239], v241 offset:52224
	ds_read_b128 v[212:215], v240 offset:50176
	ds_read_b128 v[216:219], v240 offset:51200
	ds_read_b128 v[220:223], v240 offset:52224
	s_waitcnt lgkmcnt(6)
	v_mfma_f32_16x16x32_bf16 v[2:5], v[224:227], v[208:211], v[2:5]
	s_waitcnt lgkmcnt(5)
	v_mfma_f32_16x16x32_bf16 v[6:9], v[228:231], v[208:211], v[6:9]
	s_waitcnt lgkmcnt(4)
	v_mfma_f32_16x16x32_bf16 v[10:13], v[232:235], v[208:211], v[10:13]
	s_waitcnt lgkmcnt(3)
	v_mfma_f32_16x16x32_bf16 v[14:17], v[236:239], v[208:211], v[14:17]
	s_waitcnt lgkmcnt(2)
	v_mfma_f32_16x16x32_bf16 v[18:21], v[224:227], v[212:215], v[18:21]
	v_mfma_f32_16x16x32_bf16 v[22:25], v[228:231], v[212:215], v[22:25]
	v_mfma_f32_16x16x32_bf16 v[26:29], v[232:235], v[212:215], v[26:29]
	v_mfma_f32_16x16x32_bf16 v[30:33], v[236:239], v[212:215], v[30:33]
	s_waitcnt lgkmcnt(1)
	v_mfma_f32_16x16x32_bf16 v[34:37], v[224:227], v[216:219], v[34:37]
	v_mfma_f32_16x16x32_bf16 v[38:41], v[228:231], v[216:219], v[38:41]
	v_mfma_f32_16x16x32_bf16 v[42:45], v[232:235], v[216:219], v[42:45]
	v_mfma_f32_16x16x32_bf16 v[46:49], v[236:239], v[216:219], v[46:49]
	s_waitcnt lgkmcnt(0)
	v_mfma_f32_16x16x32_bf16 v[50:53], v[224:227], v[220:223], v[50:53]
	v_mfma_f32_16x16x32_bf16 v[54:57], v[228:231], v[220:223], v[54:57]
	v_mfma_f32_16x16x32_bf16 v[58:61], v[232:235], v[220:223], v[58:61]
	v_mfma_f32_16x16x32_bf16 v[62:65], v[236:239], v[220:223], v[62:65]
	s_mov_b64 s[28:29], s[48:49]
	s_mov_b64 s[30:31], s[50:51]
	ds_read_b32 v162, v250 offset:0
	ds_read_b32 v163, v250 offset:64
	ds_read_b32 v164, v250 offset:128
	ds_read_b32 v165, v250 offset:192
	s_waitcnt lgkmcnt(0)
; DI unsigned pk2(float a, float b) { f2_t v = {a, b}; bf2_t r = __builtin_convertvector(v, bf2_t); return __builtin_bit_cast(unsigned, r); }
; DI void tile_branch(const Params& p, int l, int tile, char* smem) {
;     ...
; #pragma unroll
;       for (int mt = 0; mt < 2; ++mt)
; #pragma unroll
;         for (int g4 = 0; g4 < 4; ++g4) {
;           const f32x4 r4 = *(const f32x4*)&rinv_s[wm * 64 + mt * 32 + 8 * g4 + 4 * hi];
; #pragma unroll
;           for (int nt = 0; nt < 2; ++nt) {
;             const float s0 = 1.f / (1.f + __expf(-accg[mt][nt][4 * g4 + 0] * r4[0])), s1 = 1.f / (1.f + __expf(-accg[mt][nt][4 * g4 + 1] * r4[1]));
;             const float s2 = 1.f / (1.f + __expf(-accg[mt][nt][4 * g4 + 2] * r4[2])), s3 = 1.f / (1.f + __expf(-accg[mt][nt][4 * g4 + 3] * r4[3]));
;             gpk[mt][nt][2 * g4] = pk2(s0, s1); gpk[mt][nt][2 * g4 + 1] = pk2(s2, s3);
;           }
;         }
	v_mul_f32_e32 v162, 0xbfb8aa3b, v162
	v_mul_f32_e32 v163, 0xbfb8aa3b, v163
	v_mul_f32_e32 v164, 0xbfb8aa3b, v164
	v_mul_f32_e32 v165, 0xbfb8aa3b, v165
	v_mul_f32_e32 v166, v162, v2
	v_mul_f32_e32 v167, v162, v3
	v_mul_f32_e32 v168, v162, v4
	v_mul_f32_e32 v169, v162, v5
	v_exp_f32_e32 v166, v166
	v_exp_f32_e32 v167, v167
	v_exp_f32_e32 v168, v168
	v_exp_f32_e32 v169, v169
	v_add_f32_e32 v166, 1.0, v166
	v_add_f32_e32 v167, 1.0, v167
	v_add_f32_e32 v168, 1.0, v168
	v_add_f32_e32 v169, 1.0, v169
	v_rcp_f32_e32 v166, v166
	v_rcp_f32_e32 v167, v167
	v_rcp_f32_e32 v168, v168
	v_rcp_f32_e32 v169, v169
	v_cvt_pk_bf16_f32 v130, v166, v167
	v_cvt_pk_bf16_f32 v131, v168, v169
	v_mul_f32_e32 v166, v162, v6
	v_mul_f32_e32 v167, v162, v7
	v_mul_f32_e32 v168, v162, v8
	v_mul_f32_e32 v169, v162, v9
	v_exp_f32_e32 v166, v166
	v_exp_f32_e32 v167, v167
	v_exp_f32_e32 v168, v168
	v_exp_f32_e32 v169, v169
	v_add_f32_e32 v166, 1.0, v166
	v_add_f32_e32 v167, 1.0, v167
	v_add_f32_e32 v168, 1.0, v168
	v_add_f32_e32 v169, 1.0, v169
	v_rcp_f32_e32 v166, v166
	v_rcp_f32_e32 v167, v167
	v_rcp_f32_e32 v168, v168
	v_rcp_f32_e32 v169, v169
	v_cvt_pk_bf16_f32 v132, v166, v167
	v_cvt_pk_bf16_f32 v133, v168, v169
	v_mul_f32_e32 v166, v162, v10
	v_mul_f32_e32 v167, v162, v11
	v_mul_f32_e32 v168, v162, v12
	v_mul_f32_e32 v169, v162, v13
	v_exp_f32_e32 v166, v166
	v_exp_f32_e32 v167, v167
	v_exp_f32_e32 v168, v168
	v_exp_f32_e32 v169, v169
	v_add_f32_e32 v166, 1.0, v166
	v_add_f32_e32 v167, 1.0, v167
	v_add_f32_e32 v168, 1.0, v168
	v_add_f32_e32 v169, 1.0, v169
	v_rcp_f32_e32 v166, v166
	v_rcp_f32_e32 v167, v167
	v_rcp_f32_e32 v168, v168
	v_rcp_f32_e32 v169, v169
	v_cvt_pk_bf16_f32 v134, v166, v167
	v_cvt_pk_bf16_f32 v135, v168, v169
	v_mul_f32_e32 v166, v162, v14
	v_mul_f32_e32 v167, v162, v15
	v_mul_f32_e32 v168, v162, v16
	v_mul_f32_e32 v169, v162, v17
	v_exp_f32_e32 v166, v166
	v_exp_f32_e32 v167, v167
	v_exp_f32_e32 v168, v168
	v_exp_f32_e32 v169, v169
	v_add_f32_e32 v166, 1.0, v166
	v_add_f32_e32 v167, 1.0, v167
	v_add_f32_e32 v168, 1.0, v168
	v_add_f32_e32 v169, 1.0, v169
	v_rcp_f32_e32 v166, v166
	v_rcp_f32_e32 v167, v167
	v_rcp_f32_e32 v168, v168
	v_rcp_f32_e32 v169, v169
	v_cvt_pk_bf16_f32 v136, v166, v167
	v_cvt_pk_bf16_f32 v137, v168, v169
	v_mul_f32_e32 v166, v163, v18
	v_mul_f32_e32 v167, v163, v19
	v_mul_f32_e32 v168, v163, v20
	v_mul_f32_e32 v169, v163, v21
	v_exp_f32_e32 v166, v166
	v_exp_f32_e32 v167, v167
	v_exp_f32_e32 v168, v168
	v_exp_f32_e32 v169, v169
	v_add_f32_e32 v166, 1.0, v166
	v_add_f32_e32 v167, 1.0, v167
	v_add_f32_e32 v168, 1.0, v168
	v_add_f32_e32 v169, 1.0, v169
	v_rcp_f32_e32 v166, v166
	v_rcp_f32_e32 v167, v167
	v_rcp_f32_e32 v168, v168
	v_rcp_f32_e32 v169, v169
	v_cvt_pk_bf16_f32 v138, v166, v167
	v_cvt_pk_bf16_f32 v139, v168, v169
	v_mul_f32_e32 v166, v163, v22
	v_mul_f32_e32 v167, v163, v23
	v_mul_f32_e32 v168, v163, v24
	v_mul_f32_e32 v169, v163, v25
	v_exp_f32_e32 v166, v166
	v_exp_f32_e32 v167, v167
	v_exp_f32_e32 v168, v168
	v_exp_f32_e32 v169, v169
	v_add_f32_e32 v166, 1.0, v166
	v_add_f32_e32 v167, 1.0, v167
	v_add_f32_e32 v168, 1.0, v168
	v_add_f32_e32 v169, 1.0, v169
	v_rcp_f32_e32 v166, v166
	v_rcp_f32_e32 v167, v167
	v_rcp_f32_e32 v168, v168
	v_rcp_f32_e32 v169, v169
	v_cvt_pk_bf16_f32 v140, v166, v167
	v_cvt_pk_bf16_f32 v141, v168, v169
	v_mul_f32_e32 v166, v163, v26
	v_mul_f32_e32 v167, v163, v27
	v_mul_f32_e32 v168, v163, v28
	v_mul_f32_e32 v169, v163, v29
	v_exp_f32_e32 v166, v166
	v_exp_f32_e32 v167, v167
	v_exp_f32_e32 v168, v168
	v_exp_f32_e32 v169, v169
	v_add_f32_e32 v166, 1.0, v166
	v_add_f32_e32 v167, 1.0, v167
	v_add_f32_e32 v168, 1.0, v168
	v_add_f32_e32 v169, 1.0, v169
	v_rcp_f32_e32 v166, v166
	v_rcp_f32_e32 v167, v167
	v_rcp_f32_e32 v168, v168
	v_rcp_f32_e32 v169, v169
	v_cvt_pk_bf16_f32 v142, v166, v167
	v_cvt_pk_bf16_f32 v143, v168, v169
	v_mul_f32_e32 v166, v163, v30
	v_mul_f32_e32 v167, v163, v31
	v_mul_f32_e32 v168, v163, v32
	v_mul_f32_e32 v169, v163, v33
	v_exp_f32_e32 v166, v166
	v_exp_f32_e32 v167, v167
	v_exp_f32_e32 v168, v168
	v_exp_f32_e32 v169, v169
	v_add_f32_e32 v166, 1.0, v166
	v_add_f32_e32 v167, 1.0, v167
	v_add_f32_e32 v168, 1.0, v168
	v_add_f32_e32 v169, 1.0, v169
	v_rcp_f32_e32 v166, v166
	v_rcp_f32_e32 v167, v167
	v_rcp_f32_e32 v168, v168
	v_rcp_f32_e32 v169, v169
	v_cvt_pk_bf16_f32 v144, v166, v167
	v_cvt_pk_bf16_f32 v145, v168, v169
	v_mul_f32_e32 v166, v164, v34
	v_mul_f32_e32 v167, v164, v35
	v_mul_f32_e32 v168, v164, v36
	v_mul_f32_e32 v169, v164, v37
	v_exp_f32_e32 v166, v166
	v_exp_f32_e32 v167, v167
	v_exp_f32_e32 v168, v168
	v_exp_f32_e32 v169, v169
	v_add_f32_e32 v166, 1.0, v166
	v_add_f32_e32 v167, 1.0, v167
	v_add_f32_e32 v168, 1.0, v168
	v_add_f32_e32 v169, 1.0, v169
	v_rcp_f32_e32 v166, v166
	v_rcp_f32_e32 v167, v167
	v_rcp_f32_e32 v168, v168
	v_rcp_f32_e32 v169, v169
	v_cvt_pk_bf16_f32 v146, v166, v167
	v_cvt_pk_bf16_f32 v147, v168, v169
	v_mul_f32_e32 v166, v164, v38
	v_mul_f32_e32 v167, v164, v39
	v_mul_f32_e32 v168, v164, v40
	v_mul_f32_e32 v169, v164, v41
	v_exp_f32_e32 v166, v166
	v_exp_f32_e32 v167, v167
	v_exp_f32_e32 v168, v168
	v_exp_f32_e32 v169, v169
	v_add_f32_e32 v166, 1.0, v166
	v_add_f32_e32 v167, 1.0, v167
	v_add_f32_e32 v168, 1.0, v168
	v_add_f32_e32 v169, 1.0, v169
	v_rcp_f32_e32 v166, v166
	v_rcp_f32_e32 v167, v167
	v_rcp_f32_e32 v168, v168
	v_rcp_f32_e32 v169, v169
	v_cvt_pk_bf16_f32 v148, v166, v167
	v_cvt_pk_bf16_f32 v149, v168, v169
	v_mul_f32_e32 v166, v164, v42
	v_mul_f32_e32 v167, v164, v43
; DI unsigned pk2(float a, float b) { f2_t v = {a, b}; bf2_t r = __builtin_convertvector(v, bf2_t); return __builtin_bit_cast(unsigned, r); }
; #define BLOAD(A_, B_, kt) do { _Pragma("unroll") for (int i = 0; i < 4; ++i) { \
;     A_[i] = *(const u32x4*)((const char*)Ap + (aoff + (unsigned)(32 * i * lda + (kt) * 64) * 2u)); B_[i] = *(const u32x4*)((const char*)Wt + (woff + (unsigned)(32 * i * K + (kt) * 64) * 2u)); } } while (0)
; #define BLOAD(A_, B_, kt) do { _Pragma("unroll") for (int i = 0; i < 4; ++i) { \
;     A_[i] = *(const u32x4*)((const char*)Ap + (aoff + (unsigned)(32 * i * lda + (kt) * 64) * 2u)); B_[i] = *(const u32x4*)((const char*)Wt + (woff + (unsigned)(32 * i * K + (kt) * 64) * 2u)); } } while (0)
; #define BSTORE(A_, B_, buf) do { _Pragma("unroll") for (int i = 0; i < 4; ++i) { \
;     *(u32x4*)&As[(buf) * GBUF + (srow + 32 * i) * LDT + sc8] = A_[i]; \
;     *(u32x4*)&Bs[(buf) * GBUF + (srow + 32 * i) * LDT + sc8] = B_[i]; } } while (0)
; template <bool ROWNORM, int NK>
; DI void gemm_main_bf(const u16* __restrict__ Ap, int lda, const u16* __restrict__ Wt, f32x16 (&acc)[2][2], char* smem, float* rinv_s) {
;     ...
;   __builtin_amdgcn_s_setprio(0);
;   BLOAD(a0, b0, 0); BLOAD(a1, b1, 1);
;   __syncthreads();
;   BSTORE(a0, b0, 0);
;   BLOAD(a0, b0, 2);
;   __syncthreads();
; DI void tile_branch(const Params& p, int l, int tile, char* smem) {
;     ...
; #pragma unroll
;       for (int mt = 0; mt < 2; ++mt)
; #pragma unroll
;         for (int g4 = 0; g4 < 4; ++g4) {
;           const f32x4 r4 = *(const f32x4*)&rinv_s[wm * 64 + mt * 32 + 8 * g4 + 4 * hi];
; #pragma unroll
;           for (int nt = 0; nt < 2; ++nt) {
;             const float s0 = 1.f / (1.f + __expf(-accg[mt][nt][4 * g4 + 0] * r4[0])), s1 = 1.f / (1.f + __expf(-accg[mt][nt][4 * g4 + 1] * r4[1]));
;             const float s2 = 1.f / (1.f + __expf(-accg[mt][nt][4 * g4 + 2] * r4[2])), s3 = 1.f / (1.f + __expf(-accg[mt][nt][4 * g4 + 3] * r4[3]));
;             gpk[mt][nt][2 * g4] = pk2(s0, s1); gpk[mt][nt][2 * g4 + 1] = pk2(s2, s3);
;           }
;         }
;     }
;     f32x16 acc[2][2]; zero_acc(acc);
;     gemm_main_bf<false, 8>((const u16*)(p.ws + OFF_BR) + (size_t)(br * CT + m0) * 512, 512,
	v_mul_f32_e32 v168, v164, v44
	v_mul_f32_e32 v169, v164, v45
	v_exp_f32_e32 v166, v166
	v_exp_f32_e32 v167, v167
	v_exp_f32_e32 v168, v168
	v_exp_f32_e32 v169, v169
	v_add_f32_e32 v166, 1.0, v166
	v_add_f32_e32 v167, 1.0, v167
	v_add_f32_e32 v168, 1.0, v168
	v_add_f32_e32 v169, 1.0, v169
	v_rcp_f32_e32 v166, v166
	v_rcp_f32_e32 v167, v167
	v_rcp_f32_e32 v168, v168
	v_rcp_f32_e32 v169, v169
	v_cvt_pk_bf16_f32 v150, v166, v167
	v_cvt_pk_bf16_f32 v151, v168, v169
	v_mul_f32_e32 v166, v164, v46
	v_mul_f32_e32 v167, v164, v47
	v_mul_f32_e32 v168, v164, v48
	v_mul_f32_e32 v169, v164, v49
	v_exp_f32_e32 v166, v166
	v_exp_f32_e32 v167, v167
	v_exp_f32_e32 v168, v168
	v_exp_f32_e32 v169, v169
	v_add_f32_e32 v166, 1.0, v166
	v_add_f32_e32 v167, 1.0, v167
	v_add_f32_e32 v168, 1.0, v168
	v_add_f32_e32 v169, 1.0, v169
	v_rcp_f32_e32 v166, v166
	v_rcp_f32_e32 v167, v167
	v_rcp_f32_e32 v168, v168
	v_rcp_f32_e32 v169, v169
	v_cvt_pk_bf16_f32 v152, v166, v167
	v_cvt_pk_bf16_f32 v153, v168, v169
	v_mul_f32_e32 v166, v165, v50
	v_mul_f32_e32 v167, v165, v51
	v_mul_f32_e32 v168, v165, v52
	v_mul_f32_e32 v169, v165, v53
	v_exp_f32_e32 v166, v166
	v_exp_f32_e32 v167, v167
	v_exp_f32_e32 v168, v168
	v_exp_f32_e32 v169, v169
	v_add_f32_e32 v166, 1.0, v166
	v_add_f32_e32 v167, 1.0, v167
	v_add_f32_e32 v168, 1.0, v168
	v_add_f32_e32 v169, 1.0, v169
	v_rcp_f32_e32 v166, v166
	v_rcp_f32_e32 v167, v167
	v_rcp_f32_e32 v168, v168
	v_rcp_f32_e32 v169, v169
	v_cvt_pk_bf16_f32 v154, v166, v167
	v_cvt_pk_bf16_f32 v155, v168, v169
	v_mul_f32_e32 v166, v165, v54
	v_mul_f32_e32 v167, v165, v55
	v_mul_f32_e32 v168, v165, v56
	v_mul_f32_e32 v169, v165, v57
	v_exp_f32_e32 v166, v166
	v_exp_f32_e32 v167, v167
	v_exp_f32_e32 v168, v168
	v_exp_f32_e32 v169, v169
	v_add_f32_e32 v166, 1.0, v166
	v_add_f32_e32 v167, 1.0, v167
	v_add_f32_e32 v168, 1.0, v168
	v_add_f32_e32 v169, 1.0, v169
	v_rcp_f32_e32 v166, v166
	v_rcp_f32_e32 v167, v167
	v_rcp_f32_e32 v168, v168
	v_rcp_f32_e32 v169, v169
	v_cvt_pk_bf16_f32 v156, v166, v167
	v_cvt_pk_bf16_f32 v157, v168, v169
	v_mul_f32_e32 v166, v165, v58
	v_mul_f32_e32 v167, v165, v59
	v_mul_f32_e32 v168, v165, v60
	v_mul_f32_e32 v169, v165, v61
	v_exp_f32_e32 v166, v166
	v_exp_f32_e32 v167, v167
	v_exp_f32_e32 v168, v168
	v_exp_f32_e32 v169, v169
	v_add_f32_e32 v166, 1.0, v166
	v_add_f32_e32 v167, 1.0, v167
	v_add_f32_e32 v168, 1.0, v168
	v_add_f32_e32 v169, 1.0, v169
	v_rcp_f32_e32 v166, v166
	v_rcp_f32_e32 v167, v167
	v_rcp_f32_e32 v168, v168
	v_rcp_f32_e32 v169, v169
	v_cvt_pk_bf16_f32 v158, v166, v167
	v_cvt_pk_bf16_f32 v159, v168, v169
	v_mul_f32_e32 v166, v165, v62
	v_mul_f32_e32 v167, v165, v63
	v_mul_f32_e32 v168, v165, v64
	v_mul_f32_e32 v169, v165, v65
	v_exp_f32_e32 v166, v166
	v_exp_f32_e32 v167, v167
	v_exp_f32_e32 v168, v168
	v_exp_f32_e32 v169, v169
	v_add_f32_e32 v166, 1.0, v166
	v_add_f32_e32 v167, 1.0, v167
	v_add_f32_e32 v168, 1.0, v168
	v_add_f32_e32 v169, 1.0, v169
	v_rcp_f32_e32 v166, v166
	v_rcp_f32_e32 v167, v167
	v_rcp_f32_e32 v168, v168
	v_rcp_f32_e32 v169, v169
	v_cvt_pk_bf16_f32 v160, v166, v167
	v_cvt_pk_bf16_f32 v161, v168, v169
	s_add_u32 m0, s52, 0x0
	s_nop 0
	global_load_lds_dwordx4 v244, s[28:29]
	global_load_lds_dwordx4 v245, s[28:29] offset:1024
	s_add_u32 m0, s53, 0x0
	s_nop 0
	global_load_lds_dwordx4 v251, s[30:31]
	global_load_lds_dwordx4 v251, s[30:31] offset:1024
	s_add_u32 m0, s52, 0x4000
	s_add_u32 s28, s28, 0x40
	s_addc_u32 s29, s29, 0
	global_load_lds_dwordx4 v244, s[28:29]
	global_load_lds_dwordx4 v245, s[28:29] offset:1024
	s_add_u32 m0, s53, 0x4000
	s_add_u32 s30, s30, 0x10000
	s_addc_u32 s31, s31, 0
	global_load_lds_dwordx4 v251, s[30:31]
	global_load_lds_dwordx4 v251, s[30:31] offset:1024
	s_add_u32 m0, s52, 0x8000
	s_add_u32 s28, s28, 0x40
	s_addc_u32 s29, s29, 0
	global_load_lds_dwordx4 v244, s[28:29]
	global_load_lds_dwordx4 v245, s[28:29] offset:1024
	s_add_u32 m0, s53, 0x8000
	s_add_u32 s30, s30, 0x10000
	s_addc_u32 s31, s31, 0
	global_load_lds_dwordx4 v251, s[30:31]
	global_load_lds_dwordx4 v251, s[30:31] offset:1024
	v_mov_b32_e32 v2, 0
	v_mov_b32_e32 v3, 0
	v_mov_b32_e32 v4, 0
	v_mov_b32_e32 v5, 0
	v_mov_b32_e32 v6, 0
	v_mov_b32_e32 v7, 0
	v_mov_b32_e32 v8, 0
	v_mov_b32_e32 v9, 0
	v_mov_b32_e32 v10, 0
	v_mov_b32_e32 v11, 0
	v_mov_b32_e32 v12, 0
	v_mov_b32_e32 v13, 0
	v_mov_b32_e32 v14, 0
	v_mov_b32_e32 v15, 0
	v_mov_b32_e32 v16, 0
	v_mov_b32_e32 v17, 0
	v_mov_b32_e32 v18, 0
	v_mov_b32_e32 v19, 0
	v_mov_b32_e32 v20, 0
	v_mov_b32_e32 v21, 0
	v_mov_b32_e32 v22, 0
	v_mov_b32_e32 v23, 0
	v_mov_b32_e32 v24, 0
	v_mov_b32_e32 v25, 0
	v_mov_b32_e32 v26, 0
	v_mov_b32_e32 v27, 0
	v_mov_b32_e32 v28, 0
	v_mov_b32_e32 v29, 0
	v_mov_b32_e32 v30, 0
	v_mov_b32_e32 v31, 0
	v_mov_b32_e32 v32, 0
	v_mov_b32_e32 v33, 0
	v_mov_b32_e32 v34, 0
	v_mov_b32_e32 v35, 0
	v_mov_b32_e32 v36, 0
	v_mov_b32_e32 v37, 0
	v_mov_b32_e32 v38, 0
	v_mov_b32_e32 v39, 0
	v_mov_b32_e32 v40, 0
	v_mov_b32_e32 v41, 0
	v_mov_b32_e32 v42, 0
	v_mov_b32_e32 v43, 0
	v_mov_b32_e32 v44, 0
	v_mov_b32_e32 v45, 0
	v_mov_b32_e32 v46, 0
	v_mov_b32_e32 v47, 0
	v_mov_b32_e32 v48, 0
	v_mov_b32_e32 v49, 0
	v_mov_b32_e32 v50, 0
	v_mov_b32_e32 v51, 0
	v_mov_b32_e32 v52, 0
	v_mov_b32_e32 v53, 0
	v_mov_b32_e32 v54, 0
	v_mov_b32_e32 v55, 0
	v_mov_b32_e32 v56, 0
	v_mov_b32_e32 v57, 0
	v_mov_b32_e32 v58, 0
	v_mov_b32_e32 v59, 0
	v_mov_b32_e32 v60, 0
	v_mov_b32_e32 v61, 0
	v_mov_b32_e32 v62, 0
	v_mov_b32_e32 v63, 0
	v_mov_b32_e32 v64, 0
	v_mov_b32_e32 v65, 0
	s_mov_b32 s74, 3
	.p2align 6

; DI int TID() { int t = (int)__builtin_amdgcn_workitem_id_x(); asm volatile("" : "+v"(t)); return t; }
; template <int DQK, int DV, bool BAND> ...
;   constexpr int KLD = DQK + 8, VLD = 68, ND0 = DQK / 16, NCB = DV / 32;
;   constexpr int KCPR = DQK / 8, KCH = 64 * KCPR / 256, VCH = DV * 8 / 256;
;   const int tid = TID(), lane = tid & 63, w = tid >> 6, r32 = lane & 31, hi = lane >> 5;
;   u16* Ks = (u16*)smem; u16* Vs = (u16*)(smem + 17408); float* sc = (float*)(smem + 34816) + w * 64;
;   const int qw0 = q0 + w * 32, qi = qw0 + r32;
;   bf16x8 qf[ND0];
; #pragma unroll
;   for (int d0 = 0; d0 < ND0; ++d0) qf[d0] = *(const bf16x8*)(Q + (size_t)(w * 32 + r32) * ldq + d0 * 16 + hi * 8);
;   f32x16 o[NCB];
; #pragma unroll
;   for (int cb = 0; cb < NCB; ++cb)
; #pragma unroll
;     for (int r = 0; r < 16; ++r) o[cb][r] = 0.f;
;   float m_run = -INFINITY, l_run = 0.f;
;   int kt_lo = 0, kt_hi = nkeys >> 6;
;   if (BAND) { kt_lo = max(0, (q0 >> 6) - 1); kt_hi = min(nkeys >> 6, (q0 >> 6) + 3); }
;   u32x4 kreg[KCH], vreg[VCH];
;     ...
;   constexpr bool PREF = true;
;   if (PREF) ALOAD(kt_lo);
; DI void item_attn(const Params& p, int l, const Chunk& ck, int it, char* smem) {
;   const int S = ck.S;
;   if (it < 8 * MTN) {
;     static_assert(8 * MTN == 1024, "MLA item swizzle assumes 1024 items");
;     const int rnd = it >> 9, x = it & 7, jj = (it & 511) >> 3; const int qs = ck.sshift - 7, ppx = 64 >> qs;
;     const int bh = rnd * (8 * ppx) + x * ppx + (jj >> qs), qblk = jj & ((1 << qs) - 1);
;     const int h = bh & 7, bl = bh >> 3; const int t0 = qblk * 128, lt0 = bl * S + t0;
;     const u16* Q = (const u16*)(p.ws + OFF_QM) + (size_t)lt0 * 768 + h * 96;
;     const u16* K = (const u16*)(p.ws + OFF_KM) + (size_t)(bl * S) * 768 + h * 96;
;     const u16* Vt = (const u16*)(p.ws + OFF_VMT) + ((size_t)(bl * 8 + h) * 64) * S;
;     u16* O = (u16*)(p.ws + OFF_BR) + (size_t)(1 * CT + lt0) * 512 + h * 64;
;     (void)t0;
;     attn_block<96, 64, false>(Q, 768, K, 768, Vt, S, S, t0, 0.f, O, 512, nullptr, 0, smem);
.LBB1_317:
	s_ashr_i32 s21, s55, 6
	s_and_b32 s0, s55, 7
	s_and_b32 s29, s21, -8
	s_bfe_u32 s20, s55, 0x60003
	s_or_b32 s0, s29, s0
	s_lshr_b32 s30, s20, s35
	s_mul_i32 s0, s0, s42
	s_add_i32 s21, s0, s30
	s_and_b32 s20, s20, s43
	s_ashr_i32 s22, s21, 3
	s_lshl_b32 s20, s20, 7
	s_mul_i32 s26, s22, s2
	s_add_i32 s20, s26, s20
	s_and_b32 s28, s16, 7
	s_and_b32 s0, s21, 7
	s_mul_i32 s23, s20, 0x600
	s_mul_hi_i32 s22, s20, 0x600
	s_add_u32 s23, s93, s23
	s_addc_u32 s24, s94, s22
	s_mul_i32 s27, s0, 0xc0
	s_add_u32 s22, s23, s27
	v_mov_b32_e32 v2, v172
	s_addc_u32 s23, s24, 0
	s_mul_hi_i32 s25, s74, s21
	s_mul_i32 s24, s74, s21
	s_movk_i32 s21, 0xffe0
	v_ashrrev_i32_e32 v0, 1, v2
	v_bfe_u32 v3, v2, 5, 1
	s_waitcnt vmcnt(9)
	v_and_b32_e32 v122, 0xffffffe0, v0
	v_bfi_b32 v0, s21, v0, v2
	v_mov_b64_e32 v[4:5], s[22:23]
	s_movk_i32 s31, 0x600
	v_mad_i64_i32 v[4:5], s[22:23], v0, s31, v[4:5]
	v_lshlrev_b32_e32 v0, 4, v3
	v_lshl_add_u64 v[4:5], v[4:5], 0, v[0:1]
	global_load_dwordx4 v[66:69], v[4:5], off
	global_load_dwordx4 v[70:73], v[4:5], off offset:32
	global_load_dwordx4 v[74:77], v[4:5], off offset:64
	global_load_dwordx4 v[78:81], v[4:5], off offset:96
	global_load_dwordx4 v[82:85], v[4:5], off offset:128
	global_load_dwordx4 v[86:89], v[4:5], off offset:160
	v_lshlrev_b32_e32 v4, 2, v2
	s_mov_b32 s21, 0x2aaaaaab
	v_and_b32_e32 v29, 0xffffff00, v4
	v_mul_hi_i32 v4, v2, s21
	v_lshrrev_b32_e32 v5, 31, v4
	v_ashrrev_i32_e32 v4, 1, v4
	v_add_u32_e32 v30, v4, v5
	v_add_u32_e32 v4, 0x100, v2
	v_mul_hi_i32 v5, v4, s21
	v_lshrrev_b32_e32 v6, 31, v5
	v_ashrrev_i32_e32 v5, 1, v5
	v_add_u32_e32 v31, v5, v6
	v_add_u32_e32 v6, 0x200, v2
	s_lshl_b64 s[24:25], s[24:25], 1
	v_mul_hi_i32 v5, v6, s21
	v_ashrrev_i32_e32 v12, 3, v2
	s_waitcnt lgkmcnt(0)
	v_ashrrev_i32_e32 v16, 3, v4
	s_add_u32 s24, s17, s24
	v_lshrrev_b32_e32 v7, 31, v5
	v_ashrrev_i32_e32 v5, 1, v5
	v_mad_i64_i32 v[14:15], s[22:23], v12, s2, 0
	v_mad_i64_i32 v[18:19], s[22:23], v16, s2, 0
	s_addc_u32 s25, s34, s25
	v_add_u32_e32 v36, v5, v7
	v_lshlrev_b32_e32 v5, 4, v2
	s_mul_i32 s22, s26, 0x600
	v_and_b32_e32 v8, 0x70, v5
	v_mov_b32_e32 v9, v1
	s_mul_hi_i32 s23, s26, 0x600
	s_add_u32 s21, s79, s22
	v_lshl_add_u64 v[10:11], s[24:25], 0, v[8:9]
	s_addc_u32 s25, s92, s23
	s_add_u32 s24, s21, s27
	v_mad_u64_u32 v[6:7], s[26:27], v36, -12, v[6:7]
	s_addc_u32 s25, s25, 0
	v_lshlrev_b32_e32 v20, 3, v6
	v_mad_u64_u32 v[4:5], s[26:27], v31, -12, v[4:5]
	v_lshl_add_u64 v[18:19], v[18:19], 1, v[10:11]
	v_lshl_add_u64 v[10:11], v[14:15], 1, v[10:11]
	v_ashrrev_i32_e32 v21, 31, v20
	v_lshlrev_b32_e32 v22, 3, v4
	v_mad_u64_u32 v[24:25], s[26:27], v30, -12, v[2:3]
	global_load_dwordx4 v[94:97], v[18:19], off
	global_load_dwordx4 v[90:93], v[10:11], off
	v_mov_b64_e32 v[10:11], s[24:25]
	v_ashrrev_i32_e32 v23, 31, v22
	v_lshlrev_b32_e32 v26, 3, v24
	v_mad_i64_i32 v[14:15], s[24:25], v36, s31, v[10:11]
	v_lshlrev_b64 v[18:19], 1, v[20:21]
	v_ashrrev_i32_e32 v27, 31, v26
	v_lshl_add_u64 v[14:15], v[14:15], 0, v[18:19]
	v_mad_i64_i32 v[20:21], s[24:25], v31, s31, v[10:11]
	v_lshlrev_b64 v[22:23], 1, v[22:23]
	v_lshl_add_u64 v[20:21], v[20:21], 0, v[22:23]
	global_load_dwordx4 v[102:105], v[14:15], off
	global_load_dwordx4 v[98:101], v[20:21], off
	v_mad_i64_i32 v[10:11], s[24:25], v30, s31, v[10:11]
	v_lshlrev_b64 v[14:15], 1, v[26:27]
	v_lshl_add_u64 v[10:11], v[10:11], 0, v[14:15]
	global_load_dwordx4 v[106:109], v[10:11], off
	s_movk_i32 s24, 0xd0
	s_movk_i32 s26, 0x88
	v_mul_lo_u32 v38, v30, s24
	v_mul_lo_u32 v40, v31, s24
	v_mul_lo_u32 v42, v36, s24
	v_mad_u64_u32 v[32:33], s[24:25], v12, s26, v[8:9]
	v_mad_u64_u32 v[34:35], s[24:25], v16, s26, v[8:9]
	s_or_b32 s24, s29, s28
	s_mul_i32 s24, s42, s24
	s_add_i32 s24, s30, s24
	s_ashr_i32 s25, s24, 31
	v_and_b32_e32 v121, 31, v2
	v_ashrrev_i32_e32 v13, 31, v12
	v_or_b32_e32 v120, v29, v0
	s_lshl_b64 s[24:25], s[24:25], 7
	v_and_b32_e32 v0, 7, v2
	v_lshlrev_b32_e32 v28, 3, v3
	v_cmp_eq_u32_e64 s[36:37], 0, v3
	v_lshlrev_b32_e32 v123, 2, v3
	v_mul_u32_u24_e32 v3, 0x44, v121
	v_lshlrev_b32_e32 v39, 4, v4
	v_lshl_add_u64 v[4:5], v[12:13], 1, s[24:25]
	v_lshlrev_b32_e32 v0, 4, v0
	v_lshl_add_u32 v125, v3, 1, v28
	v_mad_u64_u32 v[2:3], s[26:27], s2, v4, v[0:1]
	v_ashrrev_i32_e32 v17, 31, v16
	v_mad_i32_i24 v3, s2, v5, v3
	s_mov_b64 s[26:27], 0x15080080
	v_lshl_add_u64 v[110:111], v[2:3], 0, s[26:27]
	v_lshl_add_u64 v[2:3], v[16:17], 1, s[24:25]
	v_mad_u64_u32 v[4:5], s[24:25], s2, v2, v[0:1]
	v_mad_i32_i24 v5, s2, v3, v5
	v_mov_b64_e32 v[2:3], s[22:23]
	v_lshl_add_u64 v[112:113], v[4:5], 0, s[26:27]
	v_mad_i64_i32 v[4:5], s[22:23], v36, s31, v[2:3]
	s_mov_b64 s[26:27], 0x13898000
	s_add_i32 s22, s54, s30
	v_lshl_add_u64 v[4:5], v[4:5], 0, s[26:27]
	s_and_b32 s24, s22, 7
	v_mad_u64_u32 v[4:5], s[22:23], s24, v203, v[4:5]
	s_waitcnt vmcnt(19)
; template <int DQK, int DV, bool BAND> ...
;     ...
;   const int qw0 = q0 + w * 32, qi = qw0 + r32;
;   bf16x8 qf[ND0];
; #pragma unroll
;   for (int d0 = 0; d0 < ND0; ++d0) qf[d0] = *(const bf16x8*)(Q + (size_t)(w * 32 + r32) * ldq + d0 * 16 + hi * 8);
;   f32x16 o[NCB];
; #pragma unroll
;   for (int cb = 0; cb < NCB; ++cb)
; #pragma unroll
;     for (int r = 0; r < 16; ++r) o[cb][r] = 0.f;
;   float m_run = -INFINITY, l_run = 0.f;
;   int kt_lo = 0, kt_hi = nkeys >> 6;
;   if (BAND) { kt_lo = max(0, (q0 >> 6) - 1); kt_hi = min(nkeys >> 6, (q0 >> 6) + 3); }
;   u32x4 kreg[KCH], vreg[VCH];
;     ...
;   constexpr bool PREF = true;
;   if (PREF) ALOAD(kt_lo);
	v_lshl_add_u64 v[114:115], v[4:5], 0, v[18:19]
	v_mad_i64_i32 v[4:5], s[22:23], v31, s31, v[2:3]
	v_mad_i64_i32 v[2:3], s[22:23], v30, s31, v[2:3]
	v_lshl_add_u64 v[4:5], v[4:5], 0, s[26:27]
	v_lshl_add_u64 v[2:3], v[2:3], 0, s[26:27]
	v_mad_u64_u32 v[4:5], s[22:23], s24, v203, v[4:5]
	v_mad_u64_u32 v[2:3], s[22:23], s24, v203, v[2:3]
	v_lshl_or_b32 v124, v121, 2, v29
	v_lshlrev_b32_e32 v37, 4, v24
	v_lshlrev_b32_e32 v41, 4, v6
	v_add_u32_e32 v33, v28, v28
	v_mul_u32_u24_e32 v35, 0xd0, v121
	v_lshl_add_u64 v[116:117], v[4:5], 0, v[22:23]
	v_lshl_add_u64 v[118:119], v[2:3], 0, v[14:15]
	v_mov_b32_e32 v2, v1
	v_mov_b32_e32 v3, v1
	v_mov_b32_e32 v4, v1
	v_mov_b32_e32 v5, v1
	v_mov_b32_e32 v6, v1
	v_mov_b32_e32 v7, v1
	v_mov_b32_e32 v8, v1
	v_mov_b32_e32 v10, v1
	v_mov_b32_e32 v11, v1
	v_mov_b32_e32 v12, v1
	v_mov_b32_e32 v13, v1
	v_mov_b32_e32 v14, v1
	v_mov_b32_e32 v15, v1
	v_mov_b32_e32 v16, v1
	v_mov_b32_e32 v17, v1
	v_mov_b32_e32 v18, v1
	v_mov_b32_e32 v19, v1
	v_mov_b32_e32 v20, v1
	v_mov_b32_e32 v21, v1
	v_mov_b32_e32 v22, v1
	v_mov_b32_e32 v23, v1
	v_mov_b32_e32 v24, v1
	v_mov_b32_e32 v25, v1
	v_mov_b32_e32 v26, v1
	v_mov_b32_e32 v27, v1
	v_mov_b32_e32 v28, v1
	v_mov_b32_e32 v29, v1
	v_mov_b32_e32 v30, v1
	v_mov_b32_e32 v31, v1
	v_mov_b32_e32 v0, v1
	v_add_u32_e32 v130, 0x4400, v32
	v_add_u32_e32 v132, v33, v35
	v_mov_b64_e32 v[32:33], v[30:31]
	s_mov_b32 s21, 0
	s_waitcnt vmcnt(18)
	v_mov_b32_e32 v126, 0
	v_mov_b32_e32 v133, 0xff800000
	v_add_u32_e32 v127, v37, v38
	v_add_u32_e32 v128, v39, v40
	v_add_u32_e32 v129, v41, v42
	v_add_u32_e32 v131, 0x4400, v34
	v_mov_b64_e32 v[30:31], v[28:29]
	v_mov_b64_e32 v[28:29], v[26:27]
	v_mov_b64_e32 v[26:27], v[24:25]
	v_mov_b64_e32 v[24:25], v[22:23]
	v_mov_b64_e32 v[22:23], v[20:21]
	v_mov_b64_e32 v[20:21], v[18:19]
	v_mov_b64_e32 v[18:19], v[16:17]
	v_mov_b64_e32 v[16:17], v[14:15]
	v_mov_b64_e32 v[14:15], v[12:13]
	v_mov_b64_e32 v[12:13], v[10:11]
	v_mov_b64_e32 v[10:11], v[8:9]
	v_mov_b64_e32 v[8:9], v[6:7]
	v_mov_b64_e32 v[6:7], v[4:5]
	v_mov_b64_e32 v[4:5], v[2:3]
	v_mov_b64_e32 v[2:3], v[0:1]
	v_mov_b32_e32 v150, 0
	v_mov_b32_e32 v151, 0
	v_mov_b32_e32 v152, 0
	v_mov_b32_e32 v153, 0
	v_mov_b32_e32 v154, 0
	v_mov_b32_e32 v155, 0
	v_mov_b32_e32 v156, 0
	v_mov_b32_e32 v157, 0
	v_mov_b32_e32 v158, 0
	v_mov_b32_e32 v159, 0
	v_mov_b32_e32 v160, 0
	v_mov_b32_e32 v161, 0
	v_mov_b32_e32 v162, 0
	v_mov_b32_e32 v163, 0
	v_mov_b32_e32 v164, 0
	v_mov_b32_e32 v165, 0
	v_add_u32_e32 v166, 0x4000, v125
	v_add_u32_e32 v167, 0x5000, v125
	s_mov_b64 s[12:13], s[18:19]
	s_mov_b64 s[14:15], s[18:19]
	.p2align 6

; #define BLOAD(A_, B_, kt) do { _Pragma("unroll") for (int i = 0; i < 4; ++i) { \
;     A_[i] = *(const u32x4*)((const char*)Ap + (aoff + (unsigned)(32 * i * lda + (kt) * 64) * 2u)); B_[i] = *(const u32x4*)((const char*)Wt + (woff + (unsigned)(32 * i * K + (kt) * 64) * 2u)); } } while (0)
; DI RowSS rowss_load(const float* ps, int m0) { const int tid = TID(); const float* q = ps + (size_t)(m0 + (tid >> 1)) * 16 + (tid & 1) * 8; RowSS r; r.a = *(const f32x4*)q; r.b = *(const f32x4*)(q + 4); return r; }
; #define BLOAD(A_, B_, kt) do { _Pragma("unroll") for (int i = 0; i < 4; ++i) { \
;     A_[i] = *(const u32x4*)((const char*)Ap + (aoff + (unsigned)(32 * i * lda + (kt) * 64) * 2u)); B_[i] = *(const u32x4*)((const char*)Wt + (woff + (unsigned)(32 * i * K + (kt) * 64) * 2u)); } } while (0)
; #define BSTORE(A_, B_, buf) do { _Pragma("unroll") for (int i = 0; i < 4; ++i) { \
;     *(u32x4*)&As[(buf) * GBUF + (srow + 32 * i) * LDT + sc8] = A_[i]; \
;     *(u32x4*)&Bs[(buf) * GBUF + (srow + 32 * i) * LDT + sc8] = B_[i]; } } while (0)
; template <int NK>
; DI void gemm_run(PF& pf, const u16* __restrict__ Ap, int lda, const u16* __restrict__ Wt, f32x16 (&acc)[2][2], char* smem) {
;     ...
;   __builtin_amdgcn_s_setprio(0);
;   __syncthreads();
;   BSTORE(pf.a0, pf.b0, 0);
;   BLOAD(pf.a0, pf.b0, 2);
;   __syncthreads();
; DI void tile_inproj(const Params& p, int l, const Chunk& ck, int tile, int next, PF& pf, char* smem) {
;   float* Cs = (float*)smem; float* rinv_s = (float*)(smem + SMEM_CS);
;   const int mi = tile & (MTN - 1), nj = tile >> MTS; const int ni = (nj < 45) ? nj : 69; const int m0 = mi * 128;
;   const u16* Ap; const u16* Wt; inproj_ptrs(p, l, tile, Ap, Wt);
;   f32x16 acc[2][2]; zero_acc(acc);
;   const RowSS rss = rowss_load((const float*)(p.ws + OFF_PSIN), m0);
;   gemm_run<16>(pf, Ap, 1024, Wt, acc, smem);
.Linp_nokr:
	s_barrier
	s_mov_b32 s15, 0
	s_cmp_lt_u32 s30, 24
	s_cbranch_scc1 .Linp_dirk
	s_cmp_gt_u32 s30, 35
	s_cbranch_scc1 .Linp_dirk
	v_mov_b32_e32 v2, 0
	v_mov_b32_e32 v3, 0
	v_mov_b32_e32 v4, 0
	v_mov_b32_e32 v5, 0
	v_mov_b32_e32 v6, 0
	v_mov_b32_e32 v7, 0
	v_mov_b32_e32 v8, 0
	v_mov_b32_e32 v9, 0
	v_mov_b32_e32 v10, 0
	v_mov_b32_e32 v11, 0
	v_mov_b32_e32 v12, 0
	v_mov_b32_e32 v13, 0
	v_mov_b32_e32 v14, 0
	v_mov_b32_e32 v15, 0
	v_mov_b32_e32 v16, 0
	v_mov_b32_e32 v17, 0
	v_mov_b32_e32 v18, 0
	v_mov_b32_e32 v19, 0
	v_mov_b32_e32 v20, 0
	v_mov_b32_e32 v21, 0
	v_mov_b32_e32 v22, 0
	v_mov_b32_e32 v23, 0
	v_mov_b32_e32 v24, 0
	v_mov_b32_e32 v25, 0
	v_mov_b32_e32 v26, 0
	v_mov_b32_e32 v27, 0
	v_mov_b32_e32 v28, 0
	v_mov_b32_e32 v29, 0
	v_mov_b32_e32 v30, 0
	v_mov_b32_e32 v31, 0
	v_mov_b32_e32 v32, 0
	v_mov_b32_e32 v33, 0
	v_mov_b32_e32 v34, 0
	v_mov_b32_e32 v35, 0
	v_mov_b32_e32 v36, 0
	v_mov_b32_e32 v37, 0
	v_mov_b32_e32 v38, 0
	v_mov_b32_e32 v39, 0
	v_mov_b32_e32 v40, 0
	v_mov_b32_e32 v41, 0
	v_mov_b32_e32 v42, 0
	v_mov_b32_e32 v43, 0
	v_mov_b32_e32 v44, 0
	v_mov_b32_e32 v45, 0
	v_mov_b32_e32 v46, 0
	v_mov_b32_e32 v47, 0
	v_mov_b32_e32 v48, 0
	v_mov_b32_e32 v49, 0
	v_mov_b32_e32 v50, 0
	v_mov_b32_e32 v51, 0
	v_mov_b32_e32 v52, 0
	v_mov_b32_e32 v53, 0
	v_mov_b32_e32 v54, 0
	v_mov_b32_e32 v55, 0
	v_mov_b32_e32 v56, 0
	v_mov_b32_e32 v57, 0
	v_mov_b32_e32 v58, 0
	v_mov_b32_e32 v59, 0
	v_mov_b32_e32 v60, 0
	v_mov_b32_e32 v61, 0
	v_mov_b32_e32 v62, 0
	v_mov_b32_e32 v63, 0
	v_mov_b32_e32 v64, 0
	v_mov_b32_e32 v65, 0
	v_mov_b32_e32 v74, 0
	v_mov_b32_e32 v75, 0
	v_mov_b32_e32 v76, 0
	v_mov_b32_e32 v77, 0
	v_mov_b32_e32 v78, 0
	v_mov_b32_e32 v79, 0
	v_mov_b32_e32 v80, 0
	v_mov_b32_e32 v81, 0
	v_mov_b32_e32 v82, 0
	v_mov_b32_e32 v83, 0
	v_mov_b32_e32 v84, 0
	v_mov_b32_e32 v85, 0
	v_mov_b32_e32 v86, 0
	v_mov_b32_e32 v87, 0
	v_mov_b32_e32 v88, 0
	v_mov_b32_e32 v89, 0
	v_mov_b32_e32 v90, 0
	v_mov_b32_e32 v91, 0
	v_mov_b32_e32 v92, 0
	v_mov_b32_e32 v93, 0
	v_mov_b32_e32 v94, 0
	v_mov_b32_e32 v95, 0
	v_mov_b32_e32 v96, 0
	v_mov_b32_e32 v97, 0
	v_mov_b32_e32 v98, 0
	v_mov_b32_e32 v99, 0
	v_mov_b32_e32 v100, 0
	v_mov_b32_e32 v101, 0
	v_mov_b32_e32 v102, 0
	v_mov_b32_e32 v103, 0
	v_mov_b32_e32 v104, 0
	v_mov_b32_e32 v105, 0
	v_mov_b32_e32 v106, 0
	v_mov_b32_e32 v107, 0
	v_mov_b32_e32 v108, 0
	v_mov_b32_e32 v109, 0
	v_mov_b32_e32 v110, 0
	v_mov_b32_e32 v111, 0
	v_mov_b32_e32 v112, 0
	v_mov_b32_e32 v113, 0
	v_mov_b32_e32 v114, 0
	v_mov_b32_e32 v115, 0
	v_mov_b32_e32 v116, 0
	v_mov_b32_e32 v117, 0
	v_mov_b32_e32 v118, 0
	v_mov_b32_e32 v119, 0
	v_mov_b32_e32 v120, 0
	v_mov_b32_e32 v121, 0
	v_mov_b32_e32 v208, 0
	v_mov_b32_e32 v209, 0
	v_mov_b32_e32 v210, 0
	v_mov_b32_e32 v211, 0
	v_mov_b32_e32 v212, 0
	v_mov_b32_e32 v213, 0
	v_mov_b32_e32 v214, 0
	v_mov_b32_e32 v215, 0
	v_mov_b32_e32 v216, 0
	v_mov_b32_e32 v217, 0
	v_mov_b32_e32 v218, 0
	v_mov_b32_e32 v219, 0
	v_mov_b32_e32 v220, 0
	v_mov_b32_e32 v221, 0
	v_mov_b32_e32 v222, 0
	v_mov_b32_e32 v223, 0
	s_add_u32 m0, s46, 0x0
	s_nop 0
	global_load_lds_dwordx4 v138, s[48:49]
	global_load_lds_dwordx4 v139, s[48:49] offset:1024
	s_add_u32 m0, s47, 0x0
	s_nop 0
	global_load_lds_dwordx4 v140, s[50:51]
	global_load_lds_dwordx4 v141, s[50:51] offset:1024
	global_load_lds_dwordx4 v142, s[50:51] offset:2048
	global_load_lds_dwordx4 v143, s[50:51] offset:3072
	s_add_u32 m0, s46, 0x6000
	s_add_u32 s48, s48, 0x100000
	s_addc_u32 s49, s49, 0
	global_load_lds_dwordx4 v138, s[48:49]
	global_load_lds_dwordx4 v139, s[48:49] offset:1024
	s_add_u32 m0, s47, 0x6000
	s_add_u32 s50, s50, s13
	s_addc_u32 s51, s51, 0
	global_load_lds_dwordx4 v140, s[50:51]
	global_load_lds_dwordx4 v141, s[50:51] offset:1024
	global_load_lds_dwordx4 v142, s[50:51] offset:2048
	global_load_lds_dwordx4 v143, s[50:51] offset:3072
	s_mov_b32 s12, 10
	.p2align 6

; #define BLOAD(A_, B_, kt) do { _Pragma("unroll") for (int i = 0; i < 4; ++i) { \
;     A_[i] = *(const u32x4*)((const char*)Ap + (aoff + (unsigned)(32 * i * lda + (kt) * 64) * 2u)); B_[i] = *(const u32x4*)((const char*)Wt + (woff + (unsigned)(32 * i * K + (kt) * 64) * 2u)); } } while (0)
; DI RowSS rowss_load(const float* ps, int m0) { const int tid = TID(); const float* q = ps + (size_t)(m0 + (tid >> 1)) * 16 + (tid & 1) * 8; RowSS r; r.a = *(const f32x4*)q; r.b = *(const f32x4*)(q + 4); return r; }
; #define BLOAD(A_, B_, kt) do { _Pragma("unroll") for (int i = 0; i < 4; ++i) { \
;     A_[i] = *(const u32x4*)((const char*)Ap + (aoff + (unsigned)(32 * i * lda + (kt) * 64) * 2u)); B_[i] = *(const u32x4*)((const char*)Wt + (woff + (unsigned)(32 * i * K + (kt) * 64) * 2u)); } } while (0)
; #define BSTORE(A_, B_, buf) do { _Pragma("unroll") for (int i = 0; i < 4; ++i) { \
;     *(u32x4*)&As[(buf) * GBUF + (srow + 32 * i) * LDT + sc8] = A_[i]; \
;     *(u32x4*)&Bs[(buf) * GBUF + (srow + 32 * i) * LDT + sc8] = B_[i]; } } while (0)
; template <int NK>
; DI void gemm_run(PF& pf, const u16* __restrict__ Ap, int lda, const u16* __restrict__ Wt, f32x16 (&acc)[2][2], char* smem) {
;     ...
;   __builtin_amdgcn_s_setprio(0);
;   __syncthreads();
;   BSTORE(pf.a0, pf.b0, 0);
;   BLOAD(pf.a0, pf.b0, 2);
;   __syncthreads();
; DI void tile_inproj(const Params& p, int l, const Chunk& ck, int tile, int next, PF& pf, char* smem) {
;   float* Cs = (float*)smem; float* rinv_s = (float*)(smem + SMEM_CS);
;   const int mi = tile & (MTN - 1), nj = tile >> MTS; const int ni = (nj < 45) ? nj : 69; const int m0 = mi * 128;
;   const u16* Ap; const u16* Wt; inproj_ptrs(p, l, tile, Ap, Wt);
;   f32x16 acc[2][2]; zero_acc(acc);
;   const RowSS rss = rowss_load((const float*)(p.ws + OFF_PSIN), m0);
;   gemm_run<16>(pf, Ap, 1024, Wt, acc, smem);
.Linp_dirk:
	s_mov_b32 s15, 1
	v_mov_b32_e32 v2, 0
	v_mov_b32_e32 v3, 0
	v_mov_b32_e32 v4, 0
	v_mov_b32_e32 v5, 0
	v_mov_b32_e32 v6, 0
	v_mov_b32_e32 v7, 0
	v_mov_b32_e32 v8, 0
	v_mov_b32_e32 v9, 0
	v_mov_b32_e32 v10, 0
	v_mov_b32_e32 v11, 0
	v_mov_b32_e32 v12, 0
	v_mov_b32_e32 v13, 0
	v_mov_b32_e32 v14, 0
	v_mov_b32_e32 v15, 0
	v_mov_b32_e32 v16, 0
	v_mov_b32_e32 v17, 0
	v_mov_b32_e32 v18, 0
	v_mov_b32_e32 v19, 0
	v_mov_b32_e32 v20, 0
	v_mov_b32_e32 v21, 0
	v_mov_b32_e32 v22, 0
	v_mov_b32_e32 v23, 0
	v_mov_b32_e32 v24, 0
	v_mov_b32_e32 v25, 0
	v_mov_b32_e32 v26, 0
	v_mov_b32_e32 v27, 0
	v_mov_b32_e32 v28, 0
	v_mov_b32_e32 v29, 0
	v_mov_b32_e32 v30, 0
	v_mov_b32_e32 v31, 0
	v_mov_b32_e32 v32, 0
	v_mov_b32_e32 v33, 0
	v_mov_b32_e32 v34, 0
	v_mov_b32_e32 v35, 0
	v_mov_b32_e32 v36, 0
	v_mov_b32_e32 v37, 0
	v_mov_b32_e32 v38, 0
	v_mov_b32_e32 v39, 0
	v_mov_b32_e32 v40, 0
	v_mov_b32_e32 v41, 0
	v_mov_b32_e32 v42, 0
	v_mov_b32_e32 v43, 0
	v_mov_b32_e32 v44, 0
	v_mov_b32_e32 v45, 0
	v_mov_b32_e32 v46, 0
	v_mov_b32_e32 v47, 0
	v_mov_b32_e32 v48, 0
	v_mov_b32_e32 v49, 0
	v_mov_b32_e32 v50, 0
	v_mov_b32_e32 v51, 0
	v_mov_b32_e32 v52, 0
	v_mov_b32_e32 v53, 0
	v_mov_b32_e32 v54, 0
	v_mov_b32_e32 v55, 0
	v_mov_b32_e32 v56, 0
	v_mov_b32_e32 v57, 0
	v_mov_b32_e32 v58, 0
	v_mov_b32_e32 v59, 0
	v_mov_b32_e32 v60, 0
	v_mov_b32_e32 v61, 0
	v_mov_b32_e32 v62, 0
	v_mov_b32_e32 v63, 0
	v_mov_b32_e32 v64, 0
	v_mov_b32_e32 v65, 0
	v_mov_b32_e32 v74, 0
	v_mov_b32_e32 v75, 0
	v_mov_b32_e32 v76, 0
	v_mov_b32_e32 v77, 0
	v_mov_b32_e32 v78, 0
	v_mov_b32_e32 v79, 0
	v_mov_b32_e32 v80, 0
	v_mov_b32_e32 v81, 0
	v_mov_b32_e32 v82, 0
	v_mov_b32_e32 v83, 0
	v_mov_b32_e32 v84, 0
	v_mov_b32_e32 v85, 0
	v_mov_b32_e32 v86, 0
	v_mov_b32_e32 v87, 0
	v_mov_b32_e32 v88, 0
	v_mov_b32_e32 v89, 0
	v_mov_b32_e32 v90, 0
	v_mov_b32_e32 v91, 0
	v_mov_b32_e32 v92, 0
	v_mov_b32_e32 v93, 0
	v_mov_b32_e32 v94, 0
	v_mov_b32_e32 v95, 0
	v_mov_b32_e32 v96, 0
	v_mov_b32_e32 v97, 0
	v_mov_b32_e32 v98, 0
	v_mov_b32_e32 v99, 0
	v_mov_b32_e32 v100, 0
	v_mov_b32_e32 v101, 0
	v_mov_b32_e32 v102, 0
	v_mov_b32_e32 v103, 0
	v_mov_b32_e32 v104, 0
	v_mov_b32_e32 v105, 0
	v_mov_b32_e32 v106, 0
	v_mov_b32_e32 v107, 0
	v_mov_b32_e32 v108, 0
	v_mov_b32_e32 v109, 0
	v_mov_b32_e32 v110, 0
	v_mov_b32_e32 v111, 0
	v_mov_b32_e32 v112, 0
	v_mov_b32_e32 v113, 0
	v_mov_b32_e32 v114, 0
	v_mov_b32_e32 v115, 0
	v_mov_b32_e32 v116, 0
	v_mov_b32_e32 v117, 0
	v_mov_b32_e32 v118, 0
	v_mov_b32_e32 v119, 0
	v_mov_b32_e32 v120, 0
	v_mov_b32_e32 v121, 0
	v_mov_b32_e32 v208, 0
	v_mov_b32_e32 v209, 0
	v_mov_b32_e32 v210, 0
	v_mov_b32_e32 v211, 0
	v_mov_b32_e32 v212, 0
	v_mov_b32_e32 v213, 0
	v_mov_b32_e32 v214, 0
	v_mov_b32_e32 v215, 0
	v_mov_b32_e32 v216, 0
	v_mov_b32_e32 v217, 0
	v_mov_b32_e32 v218, 0
	v_mov_b32_e32 v219, 0
	v_mov_b32_e32 v220, 0
	v_mov_b32_e32 v221, 0
	v_mov_b32_e32 v222, 0
	v_mov_b32_e32 v223, 0
	s_add_u32 m0, s46, 0x0
	s_nop 0
	global_load_lds_dwordx4 v138, s[48:49]
	global_load_lds_dwordx4 v139, s[48:49] offset:1024
	s_add_u32 m0, s47, 0x0
	s_nop 0
	global_load_lds_dwordx4 v140, s[50:51]
	global_load_lds_dwordx4 v141, s[50:51] offset:1024
	global_load_lds_dwordx4 v142, s[50:51] offset:2048
	global_load_lds_dwordx4 v143, s[50:51] offset:3072
	s_add_u32 m0, s46, 0x6000
	s_add_u32 s48, s48, 0x100000
	s_addc_u32 s49, s49, 0
	global_load_lds_dwordx4 v138, s[48:49]
	global_load_lds_dwordx4 v139, s[48:49] offset:1024
	s_add_u32 m0, s47, 0x6000
	s_add_u32 s50, s50, s13
	s_addc_u32 s51, s51, 0
	global_load_lds_dwordx4 v140, s[50:51]
	global_load_lds_dwordx4 v141, s[50:51] offset:1024
	global_load_lds_dwordx4 v142, s[50:51] offset:2048
	global_load_lds_dwordx4 v143, s[50:51] offset:3072
	s_mov_b32 s12, 10
	.p2align 6
